# residual epilogue (out-proj, down): the four (ai,bj) load batches software-pipelined through free registers with counted waits instead of load->vmcnt(0)->compute->store x4
# speedup vs baseline: 1.0163x; 1.0018x over previous
; #define PG8_STAGE(bufoff, gbase, voff) do { _Pragma("unroll") for (int _i = 0; _i < 2; ++_i) \
;         __builtin_amdgcn_global_load_lds((const unsigned*)((const char*)(gbase) + (voff)[_i]), (PG8_LAS unsigned*)(lds + (bufoff) + ldsw + _i * 8192), 16, 0, 0); } while (0)
; #define PG8_LDA(dst, b, h) do { _Pragma("unroll") for (int m = 0; m < 4; ++m) _Pragma("unroll") for (int k = 0; k < 2; ++k) dst[m][k] = *(const PG8_LAS bf16x8*)(lds + PG8_SA(b, h) + aoff + m * 2048 + k * 1024); } while (0)
; #define PG8_LDB(dst, b, h) do { _Pragma("unroll") for (int n = 0; n < 2; ++n) _Pragma("unroll") for (int k = 0; k < 2; ++k) dst[n][k] = *(const PG8_LAS bf16x8*)(lds + PG8_SB(b, h) + boff + n * 2048 + k * 1024); } while (0)
; #define PG8_MMA(ai, bj, At, Bt) do { __builtin_amdgcn_s_setprio(1); _Pragma("unroll") for (int m = 0; m < 4; ++m) _Pragma("unroll") for (int n = 0; n < 2; ++n) _Pragma("unroll") for (int k = 0; k < 2; ++k) \
;         acc[ai][bj][m][n] = __builtin_amdgcn_mfma_f32_16x16x32_bf16(Bt[n][k], At[m][k], acc[ai][bj][m][n], 0, 0, 0); __builtin_amdgcn_s_setprio(0); } while (0)
; #define PG8_WAIT_V(n) asm volatile("s_waitcnt vmcnt(" #n ")" ::: "memory")
; #define PG8_WAIT_L(n) asm volatile("s_waitcnt lgkmcnt(" #n ")" ::: "memory")
; #define PG8_BAR __builtin_amdgcn_s_barrier()
; #define PG8_SCHED __builtin_amdgcn_sched_barrier(0)
; template <class Epi, class Sched, bool ALIGN_EPI = false, bool SP2 = false, bool ATILED = false, bool BTILED = false>
; __device__ __forceinline__ void gemm_phase(PG8_LAS unsigned char* lds, const Gemm g, const Sched& S, const Epi& E, const int tid) {
;     ...
;             PG8_LDB(B0, 0, 0); PG8_LDB(B1, 0, 1); PG8_SCHED; PG8_LDA(At, 0, 0); PG8_STAGE(PG8_SA(1, 1), a1 + hstepA, voffA);
;             PG8_WAIT_V(8); PG8_WAIT_L(0); PG8_BAR; PG8_MMA(0, 0, At, B0); PG8_MMA(0, 1, At, B1); PG8_BAR; PG8_SCHED;
;             PG8_LDA(At, 0, 1); PG8_STAGE(PG8_SB(0, 0), b2, voffB); PG8_STAGE(PG8_SB(0, 1), b2 + hstepB, voffB); PG8_STAGE(PG8_SA(0, 0), a2, voffA);
;             PG8_WAIT_V(8); PG8_WAIT_L(0); PG8_BAR; PG8_MMA(1, 0, At, B0); PG8_MMA(1, 1, At, B1); PG8_BAR; PG8_SCHED;
.LBB0_233:
	s_add_u32 s52, s28, 0x4000
	s_addc_u32 s53, s29, 0
	s_cmp_eq_u32 s72, 12
	s_cselect_b32 s56, s18, s52
	s_cselect_b32 s57, s11, s53
	s_cselect_b32 s54, s19, s25
	s_cselect_b32 s55, s9, s27
	s_add_u32 s52, s56, 0x8000
	s_addc_u32 s53, s57, 0
	s_add_i32 s73, 0, 0x10000
	s_add_i32 s76, 0, 0x14000
	v_add_u32_e32 v142, s73, v177
	v_add_u32_e32 v170, s76, v177
	ds_read_b128 v[130:133], v142
	ds_read_b128 v[134:137], v142 offset:1024
	ds_read_b128 v[138:141], v142 offset:2048
	ds_read_b128 v[142:145], v142 offset:3072
	ds_read_b128 v[146:149], v170
	ds_read_b128 v[162:165], v170 offset:1024
	ds_read_b128 v[166:169], v170 offset:2048
	ds_read_b128 v[170:173], v170 offset:3072
	v_lshl_add_u64 v[174:175], s[28:29], 0, v[158:159]
	s_add_i32 m0, s62, 0xc000
	ds_read_b128 v[180:183], v186
	ds_read_b128 v[188:191], v186 offset:1024
	ds_read_b128 v[196:199], v186 offset:2048
	ds_read_b128 v[200:203], v186 offset:3072
	ds_read_b128 v[204:207], v186 offset:4096
	ds_read_b128 v[208:211], v186 offset:5120
	ds_read_b128 v[212:215], v186 offset:6144
	ds_read_b128 v[216:219], v186 offset:7168
	global_load_lds_dwordx4 v[174:175], off
	v_lshl_add_u64 v[174:175], s[28:29], 0, v[160:161]
	s_add_i32 m0, s62, 0xe000
	s_nop 0
	global_load_lds_dwordx4 v[174:175], off
	s_waitcnt vmcnt(8)
	s_waitcnt lgkmcnt(0)
	s_barrier
	s_setprio 1
	s_waitcnt lgkmcnt(0)
	v_mfma_f32_16x16x32_bf16 v[126:129], v[130:133], v[180:183], v[126:129]
	v_mfma_f32_16x16x32_bf16 v[122:125], v[138:141], v[180:183], v[122:125]
	v_mfma_f32_16x16x32_bf16 v[118:121], v[130:133], v[196:199], v[118:121]
	v_mfma_f32_16x16x32_bf16 v[114:117], v[138:141], v[196:199], v[114:117]
	v_mfma_f32_16x16x32_bf16 v[110:113], v[130:133], v[204:207], v[110:113]
	v_mfma_f32_16x16x32_bf16 v[106:109], v[138:141], v[204:207], v[106:109]
	v_mfma_f32_16x16x32_bf16 v[102:105], v[130:133], v[212:215], v[102:105]
	v_mfma_f32_16x16x32_bf16 v[98:101], v[138:141], v[212:215], v[98:101]
	v_mfma_f32_16x16x32_bf16 v[126:129], v[134:137], v[188:191], v[126:129]
	v_mfma_f32_16x16x32_bf16 v[122:125], v[142:145], v[188:191], v[122:125]
	v_mfma_f32_16x16x32_bf16 v[118:121], v[134:137], v[200:203], v[118:121]
	v_mfma_f32_16x16x32_bf16 v[114:117], v[142:145], v[200:203], v[114:117]
	v_mfma_f32_16x16x32_bf16 v[110:113], v[134:137], v[208:211], v[110:113]
	v_mfma_f32_16x16x32_bf16 v[106:109], v[142:145], v[208:211], v[106:109]
	v_mfma_f32_16x16x32_bf16 v[102:105], v[134:137], v[216:219], v[102:105]
	v_mfma_f32_16x16x32_bf16 v[98:101], v[142:145], v[216:219], v[98:101]
	s_setprio 0
	s_setprio 1
	v_mfma_f32_16x16x32_bf16 v[94:97], v[146:149], v[180:183], v[94:97]
	v_mfma_f32_16x16x32_bf16 v[90:93], v[166:169], v[180:183], v[90:93]
	v_mfma_f32_16x16x32_bf16 v[86:89], v[146:149], v[196:199], v[86:89]
	v_mfma_f32_16x16x32_bf16 v[82:85], v[166:169], v[196:199], v[82:85]
	v_mfma_f32_16x16x32_bf16 v[78:81], v[146:149], v[204:207], v[78:81]
	v_mfma_f32_16x16x32_bf16 v[74:77], v[166:169], v[204:207], v[74:77]
	v_mfma_f32_16x16x32_bf16 v[70:73], v[146:149], v[212:215], v[70:73]
	v_mfma_f32_16x16x32_bf16 v[66:69], v[166:169], v[212:215], v[66:69]
	v_mfma_f32_16x16x32_bf16 v[94:97], v[162:165], v[188:191], v[94:97]
	v_mfma_f32_16x16x32_bf16 v[90:93], v[170:173], v[188:191], v[90:93]
	v_mfma_f32_16x16x32_bf16 v[86:89], v[162:165], v[200:203], v[86:89]
	v_mfma_f32_16x16x32_bf16 v[82:85], v[170:173], v[200:203], v[82:85]
	v_mfma_f32_16x16x32_bf16 v[78:81], v[162:165], v[208:211], v[78:81]
	v_mfma_f32_16x16x32_bf16 v[74:77], v[170:173], v[208:211], v[74:77]
	v_mfma_f32_16x16x32_bf16 v[70:73], v[162:165], v[216:219], v[70:73]
	v_mfma_f32_16x16x32_bf16 v[66:69], v[170:173], v[216:219], v[66:69]
	s_setprio 0
	s_barrier
	s_add_i32 s73, s73, s61
	v_lshl_add_u64 v[174:175], s[54:55], 0, v[152:153]
	s_mov_b32 m0, s73
	ds_read_b128 v[180:183], v186 offset:16384
	ds_read_b128 v[188:191], v186 offset:17408
	ds_read_b128 v[196:199], v186 offset:18432
	ds_read_b128 v[200:203], v186 offset:19456
	ds_read_b128 v[204:207], v186 offset:20480
	ds_read_b128 v[208:211], v186 offset:21504
	ds_read_b128 v[212:215], v186 offset:22528
	ds_read_b128 v[216:219], v186 offset:23552
	global_load_lds_dwordx4 v[174:175], off
	s_add_i32 m0, s73, 0x2000
	s_add_u32 s74, s54, 0x4000
	v_lshl_add_u64 v[174:175], s[54:55], 0, v[156:157]
	s_addc_u32 s75, s55, 0
	s_add_i32 s73, s76, s61
	global_load_lds_dwordx4 v[174:175], off
	v_lshl_add_u64 v[174:175], s[74:75], 0, v[152:153]
	s_mov_b32 m0, s73
	s_nop 0
	global_load_lds_dwordx4 v[174:175], off
	v_lshl_add_u64 v[174:175], s[74:75], 0, v[156:157]
	s_add_i32 m0, s73, 0x2000
	s_nop 0
	global_load_lds_dwordx4 v[174:175], off
	v_lshl_add_u64 v[174:175], s[56:57], 0, v[150:151]
	s_mov_b32 m0, s62
	s_nop 0
	global_load_lds_dwordx4 v[174:175], off
	v_lshl_add_u64 v[174:175], s[56:57], 0, v[154:155]
	s_mov_b32 m0, s63
	s_nop 0
	global_load_lds_dwordx4 v[174:175], off
	s_waitcnt vmcnt(8)
	s_waitcnt lgkmcnt(0)
	s_barrier
; #define PG8_STAGE(bufoff, gbase, voff) do { _Pragma("unroll") for (int _i = 0; _i < 2; ++_i) \
;         __builtin_amdgcn_global_load_lds((const unsigned*)((const char*)(gbase) + (voff)[_i]), (PG8_LAS unsigned*)(lds + (bufoff) + ldsw + _i * 8192), 16, 0, 0); } while (0)
; #define PG8_LDA(dst, b, h) do { _Pragma("unroll") for (int m = 0; m < 4; ++m) _Pragma("unroll") for (int k = 0; k < 2; ++k) dst[m][k] = *(const PG8_LAS bf16x8*)(lds + PG8_SA(b, h) + aoff + m * 2048 + k * 1024); } while (0)
; #define PG8_LDB(dst, b, h) do { _Pragma("unroll") for (int n = 0; n < 2; ++n) _Pragma("unroll") for (int k = 0; k < 2; ++k) dst[n][k] = *(const PG8_LAS bf16x8*)(lds + PG8_SB(b, h) + boff + n * 2048 + k * 1024); } while (0)
; #define PG8_MMA(ai, bj, At, Bt) do { __builtin_amdgcn_s_setprio(1); _Pragma("unroll") for (int m = 0; m < 4; ++m) _Pragma("unroll") for (int n = 0; n < 2; ++n) _Pragma("unroll") for (int k = 0; k < 2; ++k) \
;         acc[ai][bj][m][n] = __builtin_amdgcn_mfma_f32_16x16x32_bf16(Bt[n][k], At[m][k], acc[ai][bj][m][n], 0, 0, 0); __builtin_amdgcn_s_setprio(0); } while (0)
; #define PG8_WAIT_V(n) asm volatile("s_waitcnt vmcnt(" #n ")" ::: "memory")
; #define PG8_WAIT_L(n) asm volatile("s_waitcnt lgkmcnt(" #n ")" ::: "memory")
; #define PG8_BAR __builtin_amdgcn_s_barrier()
; #define PG8_SCHED __builtin_amdgcn_sched_barrier(0)
; template <class Epi, class Sched, bool ALIGN_EPI = false, bool SP2 = false, bool ATILED = false, bool BTILED = false>
; __device__ __forceinline__ void gemm_phase(PG8_LAS unsigned char* lds, const Gemm g, const Sched& S, const Epi& E, const int tid) {
;     ...
;             PG8_WAIT_V(8); PG8_WAIT_L(0); PG8_BAR; PG8_MMA(1, 0, At, B0); PG8_MMA(1, 1, At, B1); PG8_BAR; PG8_SCHED;
;             PG8_LDB(B0, 1, 0); PG8_LDB(B1, 1, 1); PG8_SCHED; PG8_LDA(At, 1, 0); PG8_STAGE(PG8_SA(0, 1), a2 + hstepA, voffA);
;             PG8_WAIT_V(8); PG8_WAIT_L(0); PG8_BAR; PG8_MMA(0, 0, At, B0); PG8_MMA(0, 1, At, B1); PG8_BAR; PG8_SCHED;
;             PG8_LDA(At, 1, 1); PG8_STAGE(PG8_SB(1, 0), b3, voffB); PG8_STAGE(PG8_SB(1, 1), b3 + hstepB, voffB); PG8_STAGE(PG8_SA(1, 0), a3, voffA);
	s_setprio 1
	s_waitcnt lgkmcnt(0)
	v_mfma_f32_16x16x32_bf16 v[62:65], v[130:133], v[180:183], v[62:65]
	v_mfma_f32_16x16x32_bf16 v[58:61], v[138:141], v[180:183], v[58:61]
	v_mfma_f32_16x16x32_bf16 v[54:57], v[130:133], v[196:199], v[54:57]
	v_mfma_f32_16x16x32_bf16 v[50:53], v[138:141], v[196:199], v[50:53]
	v_mfma_f32_16x16x32_bf16 v[46:49], v[130:133], v[204:207], v[46:49]
	v_mfma_f32_16x16x32_bf16 v[42:45], v[138:141], v[204:207], v[42:45]
	v_mfma_f32_16x16x32_bf16 v[38:41], v[130:133], v[212:215], v[38:41]
	v_mfma_f32_16x16x32_bf16 v[34:37], v[138:141], v[212:215], v[34:37]
	v_mfma_f32_16x16x32_bf16 v[62:65], v[134:137], v[188:191], v[62:65]
	v_mfma_f32_16x16x32_bf16 v[58:61], v[142:145], v[188:191], v[58:61]
	v_mfma_f32_16x16x32_bf16 v[54:57], v[134:137], v[200:203], v[54:57]
	v_mfma_f32_16x16x32_bf16 v[50:53], v[142:145], v[200:203], v[50:53]
	v_mfma_f32_16x16x32_bf16 v[46:49], v[134:137], v[208:211], v[46:49]
	v_mfma_f32_16x16x32_bf16 v[42:45], v[142:145], v[208:211], v[42:45]
	v_mfma_f32_16x16x32_bf16 v[38:41], v[134:137], v[216:219], v[38:41]
	v_mfma_f32_16x16x32_bf16 v[34:37], v[142:145], v[216:219], v[34:37]
	s_setprio 0
	s_setprio 1
	v_mfma_f32_16x16x32_bf16 v[30:33], v[146:149], v[180:183], v[30:33]
	v_mfma_f32_16x16x32_bf16 v[26:29], v[166:169], v[180:183], v[26:29]
	v_mfma_f32_16x16x32_bf16 v[22:25], v[146:149], v[196:199], v[22:25]
	v_mfma_f32_16x16x32_bf16 v[18:21], v[166:169], v[196:199], v[18:21]
	v_mfma_f32_16x16x32_bf16 v[14:17], v[146:149], v[204:207], v[14:17]
	v_mfma_f32_16x16x32_bf16 v[10:13], v[166:169], v[204:207], v[10:13]
	v_mfma_f32_16x16x32_bf16 v[6:9], v[146:149], v[212:215], v[6:9]
	v_mfma_f32_16x16x32_bf16 v[2:5], v[166:169], v[212:215], v[2:5]
	v_mfma_f32_16x16x32_bf16 v[30:33], v[162:165], v[188:191], v[30:33]
	v_mfma_f32_16x16x32_bf16 v[26:29], v[170:173], v[188:191], v[26:29]
	v_mfma_f32_16x16x32_bf16 v[22:25], v[162:165], v[200:203], v[22:25]
	v_mfma_f32_16x16x32_bf16 v[18:21], v[170:173], v[200:203], v[18:21]
	v_mfma_f32_16x16x32_bf16 v[14:17], v[162:165], v[208:211], v[14:17]
	v_mfma_f32_16x16x32_bf16 v[10:13], v[170:173], v[208:211], v[10:13]
	v_mfma_f32_16x16x32_bf16 v[6:9], v[162:165], v[216:219], v[6:9]
	v_mfma_f32_16x16x32_bf16 v[2:5], v[170:173], v[216:219], v[2:5]
	s_setprio 0
	s_barrier
	s_add_i32 s73, 0, 0x18000
	s_add_i32 s74, 0, 0x1c000
	v_add_u32_e32 v142, s73, v177
	v_add_u32_e32 v170, s74, v177
	ds_read_b128 v[130:133], v142
	ds_read_b128 v[134:137], v142 offset:1024
	ds_read_b128 v[138:141], v142 offset:2048
	ds_read_b128 v[142:145], v142 offset:3072
	ds_read_b128 v[146:149], v170
	ds_read_b128 v[162:165], v170 offset:1024
	ds_read_b128 v[166:169], v170 offset:2048
	ds_read_b128 v[170:173], v170 offset:3072
	s_add_u32 s56, s56, 0x4000
	s_addc_u32 s57, s57, 0
	s_mov_b32 m0, s64
	v_lshl_add_u64 v[174:175], s[56:57], 0, v[150:151]
	ds_read_b128 v[180:183], v186 offset:32768
	ds_read_b128 v[188:191], v186 offset:33792
	ds_read_b128 v[196:199], v186 offset:34816
	ds_read_b128 v[200:203], v186 offset:35840
	ds_read_b128 v[204:207], v186 offset:36864
	ds_read_b128 v[208:211], v186 offset:37888
	ds_read_b128 v[212:215], v186 offset:38912
	ds_read_b128 v[216:219], v186 offset:39936
	global_load_lds_dwordx4 v[174:175], off
	v_lshl_add_u64 v[174:175], s[56:57], 0, v[154:155]
	s_mov_b32 m0, s65
	s_nop 0
	global_load_lds_dwordx4 v[174:175], off
	s_waitcnt vmcnt(8)
	s_waitcnt lgkmcnt(0)
	s_barrier
	s_setprio 1
	s_waitcnt lgkmcnt(0)
	v_mfma_f32_16x16x32_bf16 v[126:129], v[130:133], v[180:183], v[126:129]
	v_mfma_f32_16x16x32_bf16 v[122:125], v[138:141], v[180:183], v[122:125]
	v_mfma_f32_16x16x32_bf16 v[118:121], v[130:133], v[196:199], v[118:121]
	v_mfma_f32_16x16x32_bf16 v[114:117], v[138:141], v[196:199], v[114:117]
	v_mfma_f32_16x16x32_bf16 v[110:113], v[130:133], v[204:207], v[110:113]
	v_mfma_f32_16x16x32_bf16 v[106:109], v[138:141], v[204:207], v[106:109]
	v_mfma_f32_16x16x32_bf16 v[102:105], v[130:133], v[212:215], v[102:105]
	v_mfma_f32_16x16x32_bf16 v[98:101], v[138:141], v[212:215], v[98:101]
	v_mfma_f32_16x16x32_bf16 v[126:129], v[134:137], v[188:191], v[126:129]
	v_mfma_f32_16x16x32_bf16 v[122:125], v[142:145], v[188:191], v[122:125]
	v_mfma_f32_16x16x32_bf16 v[118:121], v[134:137], v[200:203], v[118:121]
	v_mfma_f32_16x16x32_bf16 v[114:117], v[142:145], v[200:203], v[114:117]
	v_mfma_f32_16x16x32_bf16 v[110:113], v[134:137], v[208:211], v[110:113]
	v_mfma_f32_16x16x32_bf16 v[106:109], v[142:145], v[208:211], v[106:109]
	v_mfma_f32_16x16x32_bf16 v[102:105], v[134:137], v[216:219], v[102:105]
	v_mfma_f32_16x16x32_bf16 v[98:101], v[142:145], v[216:219], v[98:101]
	s_setprio 0
	s_setprio 1
	v_mfma_f32_16x16x32_bf16 v[94:97], v[146:149], v[180:183], v[94:97]
	v_mfma_f32_16x16x32_bf16 v[90:93], v[166:169], v[180:183], v[90:93]
	v_mfma_f32_16x16x32_bf16 v[86:89], v[146:149], v[196:199], v[86:89]
	v_mfma_f32_16x16x32_bf16 v[82:85], v[166:169], v[196:199], v[82:85]
	v_mfma_f32_16x16x32_bf16 v[78:81], v[146:149], v[204:207], v[78:81]
	v_mfma_f32_16x16x32_bf16 v[74:77], v[166:169], v[204:207], v[74:77]
	v_mfma_f32_16x16x32_bf16 v[70:73], v[146:149], v[212:215], v[70:73]
	v_mfma_f32_16x16x32_bf16 v[66:69], v[166:169], v[212:215], v[66:69]
	v_mfma_f32_16x16x32_bf16 v[94:97], v[162:165], v[188:191], v[94:97]
	v_mfma_f32_16x16x32_bf16 v[90:93], v[170:173], v[188:191], v[90:93]
	v_mfma_f32_16x16x32_bf16 v[86:89], v[162:165], v[200:203], v[86:89]
	v_mfma_f32_16x16x32_bf16 v[82:85], v[170:173], v[200:203], v[82:85]
	v_mfma_f32_16x16x32_bf16 v[78:81], v[162:165], v[208:211], v[78:81]
	v_mfma_f32_16x16x32_bf16 v[74:77], v[170:173], v[208:211], v[74:77]
	v_mfma_f32_16x16x32_bf16 v[70:73], v[162:165], v[216:219], v[70:73]
	v_mfma_f32_16x16x32_bf16 v[66:69], v[170:173], v[216:219], v[66:69]
	s_setprio 0
	s_barrier
; #define PG8_STAGE(bufoff, gbase, voff) do { _Pragma("unroll") for (int _i = 0; _i < 2; ++_i) \
;         __builtin_amdgcn_global_load_lds((const unsigned*)((const char*)(gbase) + (voff)[_i]), (PG8_LAS unsigned*)(lds + (bufoff) + ldsw + _i * 8192), 16, 0, 0); } while (0)
; #define PG8_LDA(dst, b, h) do { _Pragma("unroll") for (int m = 0; m < 4; ++m) _Pragma("unroll") for (int k = 0; k < 2; ++k) dst[m][k] = *(const PG8_LAS bf16x8*)(lds + PG8_SA(b, h) + aoff + m * 2048 + k * 1024); } while (0)
; #define PG8_MMA(ai, bj, At, Bt) do { __builtin_amdgcn_s_setprio(1); _Pragma("unroll") for (int m = 0; m < 4; ++m) _Pragma("unroll") for (int n = 0; n < 2; ++n) _Pragma("unroll") for (int k = 0; k < 2; ++k) \
;         acc[ai][bj][m][n] = __builtin_amdgcn_mfma_f32_16x16x32_bf16(Bt[n][k], At[m][k], acc[ai][bj][m][n], 0, 0, 0); __builtin_amdgcn_s_setprio(0); } while (0)
; #define PG8_WAIT_V(n) asm volatile("s_waitcnt vmcnt(" #n ")" ::: "memory")
; #define PG8_WAIT_L(n) asm volatile("s_waitcnt lgkmcnt(" #n ")" ::: "memory")
; #define PG8_BAR __builtin_amdgcn_s_barrier()
; #define PG8_SCHED __builtin_amdgcn_sched_barrier(0)
; template <class Epi, class Sched, bool ALIGN_EPI = false, bool SP2 = false, bool ATILED = false, bool BTILED = false>
; __device__ __forceinline__ void gemm_phase(PG8_LAS unsigned char* lds, const Gemm g, const Sched& S, const Epi& E, const int tid) {
;     ...
;             PG8_LDA(At, 1, 1); PG8_STAGE(PG8_SB(1, 0), b3, voffB); PG8_STAGE(PG8_SB(1, 1), b3 + hstepB, voffB); PG8_STAGE(PG8_SA(1, 0), a3, voffA);
;             PG8_WAIT_V(8); PG8_WAIT_L(0); PG8_BAR; PG8_MMA(1, 0, At, B0); PG8_MMA(1, 1, At, B1); PG8_BAR; PG8_SCHED;
;     __device__ __forceinline__ void operator()(const f32x4 (&acc)[2][2][4][2], const pg8::Unit& u, int wr, int wc, int fr, int fq) const {
;         const int colb = 256 * u.pn + 32 * wc + 8 * fq, row0 = 256 * u.pm + 64 * wr + fr;
; #pragma unroll
;         for (int ai = 0; ai < 2; ++ai) {
;             float ss[4] = {0.f, 0.f, 0.f, 0.f};
; #pragma unroll
;             for (int bj = 0; bj < 2; ++bj) {
;                 const int col = colb + 128 * bj;
;                 u32x4 xr[4]; f32x4 ga4[2];
; #pragma unroll
;                 for (int m = 0; m < 4; ++m) xr[m] = *(const GAS u32x4*)(xres + TX(row0 + 128 * ai + 16 * m, col));
; #pragma unroll
;                 for (int n = 0; n < 2; ++n) ga4[n] = *(const GAS f32x4*)(ga + col + 4 * n);
	s_add_u32 s56, s54, 0x8000
	s_addc_u32 s57, s55, 0
	s_add_i32 s73, s73, s61
	v_lshl_add_u64 v[174:175], s[56:57], 0, v[152:153]
	s_mov_b32 m0, s73
	ds_read_b128 v[180:183], v186 offset:49152
	ds_read_b128 v[188:191], v186 offset:50176
	ds_read_b128 v[196:199], v186 offset:51200
	ds_read_b128 v[200:203], v186 offset:52224
	ds_read_b128 v[204:207], v186 offset:53248
	ds_read_b128 v[208:211], v186 offset:54272
	ds_read_b128 v[212:215], v186 offset:55296
	ds_read_b128 v[216:219], v186 offset:56320
	global_load_lds_dwordx4 v[174:175], off
	s_add_i32 m0, s73, 0x2000
	s_add_u32 s54, s54, 0xc000
	v_lshl_add_u64 v[174:175], s[56:57], 0, v[156:157]
	s_addc_u32 s55, s55, 0
	s_add_i32 s56, s74, s61
	global_load_lds_dwordx4 v[174:175], off
	v_lshl_add_u64 v[174:175], s[54:55], 0, v[152:153]
	s_mov_b32 m0, s56
	s_nop 0
	global_load_lds_dwordx4 v[174:175], off
	v_lshl_add_u64 v[174:175], s[54:55], 0, v[156:157]
	s_add_i32 m0, s56, 0x2000
	s_nop 0
	global_load_lds_dwordx4 v[174:175], off
	v_lshl_add_u64 v[174:175], s[52:53], 0, v[150:151]
	s_mov_b32 m0, s67
	s_nop 0
	global_load_lds_dwordx4 v[174:175], off
	v_lshl_add_u64 v[174:175], s[52:53], 0, v[154:155]
	s_mov_b32 m0, s68
	s_nop 0
	global_load_lds_dwordx4 v[174:175], off
	s_waitcnt vmcnt(8)
	s_waitcnt lgkmcnt(0)
	s_barrier
	s_setprio 1
	s_waitcnt lgkmcnt(0)
	v_mfma_f32_16x16x32_bf16 v[62:65], v[130:133], v[180:183], v[62:65]
	v_mfma_f32_16x16x32_bf16 v[58:61], v[138:141], v[180:183], v[58:61]
	v_mfma_f32_16x16x32_bf16 v[54:57], v[130:133], v[196:199], v[54:57]
	v_mfma_f32_16x16x32_bf16 v[50:53], v[138:141], v[196:199], v[50:53]
	v_mfma_f32_16x16x32_bf16 v[46:49], v[130:133], v[204:207], v[46:49]
	v_mfma_f32_16x16x32_bf16 v[42:45], v[138:141], v[204:207], v[42:45]
	v_mfma_f32_16x16x32_bf16 v[38:41], v[130:133], v[212:215], v[38:41]
	v_mfma_f32_16x16x32_bf16 v[34:37], v[138:141], v[212:215], v[34:37]
	v_mfma_f32_16x16x32_bf16 v[62:65], v[134:137], v[188:191], v[62:65]
	v_mfma_f32_16x16x32_bf16 v[58:61], v[142:145], v[188:191], v[58:61]
	v_mfma_f32_16x16x32_bf16 v[54:57], v[134:137], v[200:203], v[54:57]
	v_mfma_f32_16x16x32_bf16 v[50:53], v[142:145], v[200:203], v[50:53]
	v_mfma_f32_16x16x32_bf16 v[46:49], v[134:137], v[208:211], v[46:49]
	v_mfma_f32_16x16x32_bf16 v[42:45], v[142:145], v[208:211], v[42:45]
	v_mfma_f32_16x16x32_bf16 v[38:41], v[134:137], v[216:219], v[38:41]
	v_mfma_f32_16x16x32_bf16 v[34:37], v[142:145], v[216:219], v[34:37]
	s_setprio 0
	s_setprio 1
	v_mfma_f32_16x16x32_bf16 v[30:33], v[146:149], v[180:183], v[30:33]
	v_mfma_f32_16x16x32_bf16 v[26:29], v[166:169], v[180:183], v[26:29]
	v_mfma_f32_16x16x32_bf16 v[22:25], v[146:149], v[196:199], v[22:25]
	v_mfma_f32_16x16x32_bf16 v[18:21], v[166:169], v[196:199], v[18:21]
	v_mfma_f32_16x16x32_bf16 v[14:17], v[146:149], v[204:207], v[14:17]
	v_mfma_f32_16x16x32_bf16 v[10:13], v[166:169], v[204:207], v[10:13]
	v_mfma_f32_16x16x32_bf16 v[6:9], v[146:149], v[212:215], v[6:9]
	v_mfma_f32_16x16x32_bf16 v[2:5], v[166:169], v[212:215], v[2:5]
	v_mfma_f32_16x16x32_bf16 v[30:33], v[162:165], v[188:191], v[30:33]
	v_mfma_f32_16x16x32_bf16 v[26:29], v[170:173], v[188:191], v[26:29]
	v_mfma_f32_16x16x32_bf16 v[22:25], v[162:165], v[200:203], v[22:25]
	v_mfma_f32_16x16x32_bf16 v[18:21], v[170:173], v[200:203], v[18:21]
	v_mfma_f32_16x16x32_bf16 v[14:17], v[162:165], v[208:211], v[14:17]
	v_mfma_f32_16x16x32_bf16 v[10:13], v[170:173], v[208:211], v[10:13]
	v_mfma_f32_16x16x32_bf16 v[6:9], v[162:165], v[216:219], v[6:9]
	v_mfma_f32_16x16x32_bf16 v[2:5], v[170:173], v[216:219], v[2:5]
	s_setprio 0
	s_barrier
	s_add_i32 s72, s72, 2
	s_add_u32 s28, s28, 0x10000
	s_addc_u32 s29, s29, 0
	s_add_u32 s25, s25, 0x10000
	s_addc_u32 s27, s27, 0
	s_cmp_gt_u32 s72, 13
	s_cbranch_scc0 .LBB0_233
	s_lshl_b32 s11, s24, 8
	s_add_i32 s11, s11, s30
	s_lshl_b32 s9, s26, 8
	s_ashr_i32 s18, s11, 8
	s_or_b32 s9, s9, s66
	s_ashr_i32 s19, s18, 31
	s_lshl_b64 s[26:27], s[18:19], 12
	s_ashr_i32 s18, s9, 6
	s_ashr_i32 s19, s18, 31
	s_lshl_b64 s[24:25], s[18:19], 8
	v_or_b32_e32 v168, s9, v176
	v_bitop3_b32 v130, s9, 56, v176 bitop3:0xc8
	s_add_u32 s9, s26, s24
	v_or_b32_e32 v164, s11, v1
	v_bitop3_b32 v187, s11, v224, v1 bitop3:0xc8
	s_addc_u32 s11, s27, s25
	v_lshlrev_b32_e32 v178, 1, v130
	v_or_b32_e32 v130, s9, v187
	v_mov_b32_e32 v131, s11
	v_or_b32_e32 v190, 16, v187
	v_lshlrev_b64 v[192:193], 7, v[130:131]
	v_or_b32_e32 v130, s9, v190
	v_or_b32_e32 v188, 32, v187
	v_lshl_add_u64 v[162:163], s[20:21], 0, v[178:179]
	v_lshlrev_b64 v[174:175], 7, v[130:131]
	v_or_b32_e32 v130, s9, v188
	v_or_b32_e32 v189, 48, v187
	v_lshl_add_u64 v[132:133], v[162:163], 0, v[192:193]
	v_lshlrev_b64 v[172:173], 7, v[130:131]
	v_or_b32_e32 v130, s9, v189
	global_load_dwordx4 v[180:183], v[132:133], off
	v_subrev_u32_e32 v250, s20, v132
	v_lshl_add_u64 v[132:133], v[162:163], 0, v[174:175]
	v_lshlrev_b64 v[170:171], 7, v[130:131]
	v_ashrrev_i32_e32 v169, 31, v168
	global_load_dwordx4 v[146:149], v[132:133], off
	v_lshl_add_u64 v[132:133], v[162:163], 0, v[172:173]
	v_lshl_add_u64 v[130:131], v[162:163], 0, v[170:171]
	v_lshl_add_u64 v[166:167], v[168:169], 2, s[4:5]
	global_load_dwordx4 v[142:145], v[132:133], off
	v_lshl_add_u64 v[192:193], s[20:21], 0, v[192:193]
	global_load_dwordx4 v[130:133], v[130:131], off
	s_nop 0
	global_load_dwordx4 v[134:137], v[166:167], off offset:16
	global_load_dwordx4 v[138:141], v[166:167], off
	v_add_u32_e32 v252, 0x10000, v250
	global_load_dwordx4 v[200:203], v252, s[20:21]
	global_load_dwordx4 v[204:207], v252, s[20:21] offset:2048
	v_add_u32_e32 v252, 0x11000, v250
	global_load_dwordx4 v[208:211], v252, s[20:21]
	global_load_dwordx4 v[212:215], v252, s[20:21] offset:2048
	global_load_dwordx4 v[216:219], v[166:167], off offset:528
	global_load_dwordx4 v[150:153], v[166:167], off offset:512
	v_add_u32_e32 v252, 0x4000, v250
	global_load_dwordx4 v[154:157], v252, s[20:21]
	global_load_dwordx4 v[158:161], v252, s[20:21] offset:2048
	v_add_u32_e32 v252, 0x5000, v250
	global_load_dwordx4 v[228:231], v252, s[20:21]
	global_load_dwordx4 v[234:237], v252, s[20:21] offset:2048
	global_load_dwordx4 v[242:245], v[166:167], off offset:16
	global_load_dwordx4 v[246:249], v[166:167], off
	v_lshl_add_u64 v[192:193], v[192:193], 0, v[178:179]
	v_ashrrev_i32_e32 v165, 31, v164
	s_waitcnt vmcnt(12)
; __device__ __forceinline__ unsigned cvt_pk_bf16(float lo, float hi) { unsigned r; asm volatile("v_cvt_pk_bf16_f32 %0, %1, %2" : "=v"(r) : "v"(lo), "v"(hi)); return r; }
; #define GAS __attribute__((address_space(1)))
; __device__ __forceinline__ size_t TX(int row, int col) { return ((((size_t)(row >> 8) * 16 + (col >> 6)) * 256 + (row & 255)) << 6) + (col & 63); }
; __device__ __forceinline__ float bf2f(unsigned b) { return __uint_as_float(b << 16); }
;     __device__ __forceinline__ void operator()(const f32x4 (&acc)[2][2][4][2], const pg8::Unit& u, int wr, int wc, int fr, int fq) const {
;     ...
;                 for (int m = 0; m < 4; ++m) xr[m] = *(const GAS u32x4*)(xres + TX(row0 + 128 * ai + 16 * m, col));
; #pragma unroll
;                 for (int n = 0; n < 2; ++n) ga4[n] = *(const GAS f32x4*)(ga + col + 4 * n);
; #pragma unroll
;                 for (int m = 0; m < 4; ++m) {
;                     const size_t off = (size_t)(row0 + 128 * ai + 16 * m) * DM + col;
;                     const f32x4 x0 = {bf2f(xr[m].x & 0xffffu), bf2f(xr[m].x >> 16), bf2f(xr[m].y & 0xffffu), bf2f(xr[m].y >> 16)};
;                     const f32x4 x1 = {bf2f(xr[m].z & 0xffffu), bf2f(xr[m].z >> 16), bf2f(xr[m].w & 0xffffu), bf2f(xr[m].w >> 16)};
;                     const f32x4 n0 = x0 + ga4[0] * acc[ai][bj][m][0], n1 = x1 + ga4[1] * acc[ai][bj][m][1];
;                     if (NXT) {
;                         u32x4 w; w.x = cvt_pk_bf16(n0[0], n0[1]); w.y = cvt_pk_bf16(n0[2], n0[3]); w.z = cvt_pk_bf16(n1[0], n1[1]); w.w = cvt_pk_bf16(n1[2], n1[3]);
;                         *(GAS u32x4*)(xres + TX(row0 + 128 * ai + 16 * m, col)) = w;
;                         { const f32x4 q = n0 * n0 + n1 * n1; ss[m] += (q[0] + q[1]) + (q[2] + q[3]); }
	v_lshlrev_b32_e32 v196, 16, v180
	v_and_b32_e32 v197, 0xffff0000, v180
	v_lshlrev_b32_e32 v180, 16, v181
	v_and_b32_e32 v181, 0xffff0000, v181
	v_lshlrev_b32_e32 v198, 16, v182
	v_and_b32_e32 v199, 0xffff0000, v182
	v_lshlrev_b32_e32 v182, 16, v183
	v_and_b32_e32 v183, 0xffff0000, v183
	v_pk_fma_f32 v[128:129], v[128:129], v[140:141], v[180:181]
	v_pk_fma_f32 v[126:127], v[126:127], v[138:139], v[196:197]
	v_pk_fma_f32 v[180:181], v[124:125], v[136:137], v[182:183]
	v_pk_fma_f32 v[182:183], v[122:123], v[134:135], v[198:199]
	v_cvt_pk_bf16_f32 v122, v126, v127
	v_cvt_pk_bf16_f32 v123, v128, v129
	s_nop 0
	v_cvt_pk_bf16_f32 v124, v182, v183
	v_cvt_pk_bf16_f32 v125, v180, v181
	global_store_dwordx4 v[192:193], v[122:125], off
	s_nop 1
	v_pk_mul_f32 v[122:123], v[182:183], v[182:183]
	v_pk_mul_f32 v[124:125], v[180:181], v[180:181]
	v_pk_fma_f32 v[122:123], v[126:127], v[126:127], v[122:123]
	v_pk_fma_f32 v[124:125], v[128:129], v[128:129], v[124:125]
	v_add_f32_e32 v122, v122, v123
	v_add_f32_e32 v123, v124, v125
	v_lshlrev_b32_e32 v124, 16, v146
	v_and_b32_e32 v125, 0xffff0000, v146
	v_add_f32_e32 v191, v122, v123
	v_lshlrev_b32_e32 v122, 16, v147
	v_and_b32_e32 v123, 0xffff0000, v147
	v_lshlrev_b32_e32 v128, 16, v148
	v_and_b32_e32 v129, 0xffff0000, v148
	v_pk_fma_f32 v[124:125], v[118:119], v[138:139], v[124:125]
	v_lshl_add_u64 v[118:119], s[20:21], 0, v[174:175]
	v_lshlrev_b32_e32 v126, 16, v149
	v_and_b32_e32 v127, 0xffff0000, v149
	v_pk_fma_f32 v[122:123], v[120:121], v[140:141], v[122:123]
	v_pk_fma_f32 v[128:129], v[114:115], v[134:135], v[128:129]
	v_cvt_pk_bf16_f32 v114, v124, v125
	v_cvt_pk_bf16_f32 v115, v122, v123
	v_lshl_add_u64 v[118:119], v[118:119], 0, v[178:179]
	v_pk_fma_f32 v[126:127], v[116:117], v[136:137], v[126:127]
	v_cvt_pk_bf16_f32 v116, v128, v129
	v_lshlrev_b32_e32 v120, 16, v145
	v_cvt_pk_bf16_f32 v117, v126, v127
	global_store_dwordx4 v[118:119], v[114:117], off
	v_lshlrev_b32_e32 v118, 16, v144
	v_and_b32_e32 v119, 0xffff0000, v144
	v_lshlrev_b32_e32 v114, 16, v142
	v_and_b32_e32 v115, 0xffff0000, v142
	v_lshlrev_b32_e32 v116, 16, v143
	v_and_b32_e32 v117, 0xffff0000, v143
	v_and_b32_e32 v121, 0xffff0000, v145
	v_pk_fma_f32 v[144:145], v[110:111], v[138:139], v[114:115]
	v_lshl_add_u64 v[110:111], s[20:21], 0, v[172:173]
	v_pk_fma_f32 v[142:143], v[112:113], v[140:141], v[116:117]
	v_pk_fma_f32 v[148:149], v[106:107], v[134:135], v[118:119]
	v_cvt_pk_bf16_f32 v106, v144, v145
	v_cvt_pk_bf16_f32 v107, v142, v143
	v_lshl_add_u64 v[110:111], v[110:111], 0, v[178:179]
	v_pk_fma_f32 v[146:147], v[108:109], v[136:137], v[120:121]
	v_cvt_pk_bf16_f32 v108, v148, v149
	v_lshlrev_b32_e32 v112, 16, v133
	v_cvt_pk_bf16_f32 v109, v146, v147
	global_store_dwordx4 v[110:111], v[106:109], off
	v_lshlrev_b32_e32 v110, 16, v132
	v_and_b32_e32 v111, 0xffff0000, v132
	v_lshlrev_b32_e32 v106, 16, v130
	v_and_b32_e32 v107, 0xffff0000, v130
	v_and_b32_e32 v113, 0xffff0000, v133
	v_pk_fma_f32 v[132:133], v[102:103], v[138:139], v[106:107]
	v_lshl_add_u64 v[102:103], s[20:21], 0, v[170:171]
	v_lshlrev_b32_e32 v108, 16, v131
	v_and_b32_e32 v109, 0xffff0000, v131
	v_lshl_add_u64 v[102:103], v[102:103], 0, v[178:179]
	v_pk_fma_f32 v[130:131], v[104:105], v[140:141], v[108:109]
	v_pk_fma_f32 v[136:137], v[100:101], v[136:137], v[112:113]
	v_pk_fma_f32 v[134:135], v[98:99], v[134:135], v[110:111]
	v_cvt_pk_bf16_f32 v98, v132, v133
	v_cvt_pk_bf16_f32 v99, v130, v131
	s_nop 0
	v_cvt_pk_bf16_f32 v100, v134, v135
	v_cvt_pk_bf16_f32 v101, v136, v137
	global_store_dwordx4 v[102:103], v[98:101], off
	v_or_b32_e32 v102, 0x80, v168
	v_ashrrev_i32_e32 v103, 31, v102
	v_ashrrev_i32_e32 v98, 6, v102
	v_ashrrev_i32_e32 v99, 31, v98
	v_lshlrev_b64 v[120:121], 8, v[98:99]
	v_lshl_add_u64 v[98:99], v[120:121], 0, s[26:27]
	v_or_b32_e32 v100, v98, v187
	v_mov_b32_e32 v101, v99
	v_lshlrev_b64 v[174:175], 7, v[100:101]
	v_lshl_add_u64 v[100:101], v[162:163], 0, v[174:175]
	v_or_b32_e32 v100, v98, v190
	v_mov_b32_e32 v101, v99
	v_lshlrev_b64 v[168:169], 7, v[100:101]
	v_lshl_add_u64 v[100:101], v[162:163], 0, v[168:169]
	v_or_b32_e32 v100, v98, v188
	v_mov_b32_e32 v101, v99
	v_or_b32_e32 v98, v98, v189
	v_lshlrev_b64 v[140:141], 7, v[100:101]
	v_lshlrev_b64 v[138:139], 7, v[98:99]
	v_lshl_add_u64 v[100:101], v[162:163], 0, v[140:141]
	v_lshl_add_u64 v[98:99], v[162:163], 0, v[138:139]
	v_lshl_add_u64 v[118:119], v[102:103], 2, s[4:5]
	v_lshl_add_u64 v[174:175], s[20:21], 0, v[174:175]
	s_nop 0
	v_lshl_add_u64 v[174:175], v[174:175], 0, v[178:179]
	s_waitcnt vmcnt(10)
; __device__ __forceinline__ unsigned cvt_pk_bf16(float lo, float hi) { unsigned r; asm volatile("v_cvt_pk_bf16_f32 %0, %1, %2" : "=v"(r) : "v"(lo), "v"(hi)); return r; }
; #define GAS __attribute__((address_space(1)))
; __device__ __forceinline__ size_t TX(int row, int col) { return ((((size_t)(row >> 8) * 16 + (col >> 6)) * 256 + (row & 255)) << 6) + (col & 63); }
; __device__ __forceinline__ float bf2f(unsigned b) { return __uint_as_float(b << 16); }
;     __device__ __forceinline__ void operator()(const f32x4 (&acc)[2][2][4][2], const pg8::Unit& u, int wr, int wc, int fr, int fq) const {
;     ...
;                 for (int m = 0; m < 4; ++m) {
;                     const size_t off = (size_t)(row0 + 128 * ai + 16 * m) * DM + col;
;                     const f32x4 x0 = {bf2f(xr[m].x & 0xffffu), bf2f(xr[m].x >> 16), bf2f(xr[m].y & 0xffffu), bf2f(xr[m].y >> 16)};
;                     const f32x4 x1 = {bf2f(xr[m].z & 0xffffu), bf2f(xr[m].z >> 16), bf2f(xr[m].w & 0xffffu), bf2f(xr[m].w >> 16)};
;                     const f32x4 n0 = x0 + ga4[0] * acc[ai][bj][m][0], n1 = x1 + ga4[1] * acc[ai][bj][m][1];
;                     if (NXT) {
;                         u32x4 w; w.x = cvt_pk_bf16(n0[0], n0[1]); w.y = cvt_pk_bf16(n0[2], n0[3]); w.z = cvt_pk_bf16(n1[0], n1[1]); w.w = cvt_pk_bf16(n1[2], n1[3]);
;                         *(GAS u32x4*)(xres + TX(row0 + 128 * ai + 16 * m, col)) = w;
;                         { const f32x4 q = n0 * n0 + n1 * n1; ss[m] += (q[0] + q[1]) + (q[2] + q[3]); }
;                     } else { *(GAS f32x4*)(fout + off) = n0; *(GAS f32x4*)(fout + off + 4) = n1; }
;                 }
;             }
;             if (NXT) {
; #pragma unroll
;                 for (int m = 0; m < 4; ++m) { float s = ss[m]; s += __shfl_xor(s, 16); s += __shfl_xor(s, 32);
;                     if (fq == 0) __hip_atomic_fetch_add(ssq_out + row0 + 128 * ai + 16 * m, (unsigned)(s * 1024.0f + 0.5f), __ATOMIC_RELAXED, __HIP_MEMORY_SCOPE_AGENT); }
	v_mov_b32_e32 v170, v200
	v_mov_b32_e32 v171, v201
	v_mov_b32_e32 v172, v202
	v_mov_b32_e32 v173, v203
	v_mov_b32_e32 v114, v204
	v_mov_b32_e32 v115, v205
	v_mov_b32_e32 v116, v206
	v_mov_b32_e32 v117, v207
	v_mov_b32_e32 v106, v208
	v_mov_b32_e32 v107, v209
	v_mov_b32_e32 v108, v210
	v_mov_b32_e32 v109, v211
	v_mov_b32_e32 v98, v212
	v_mov_b32_e32 v99, v213
	v_mov_b32_e32 v100, v214
	v_mov_b32_e32 v101, v215
	v_mov_b32_e32 v102, v216
	v_mov_b32_e32 v103, v217
	v_mov_b32_e32 v104, v218
	v_mov_b32_e32 v105, v219
	v_mov_b32_e32 v110, v150
	v_mov_b32_e32 v111, v151
	v_mov_b32_e32 v112, v152
	v_mov_b32_e32 v113, v153
	v_add_u32_e32 v252, 0x14000, v250
	global_load_dwordx4 v[200:203], v252, s[20:21]
	global_load_dwordx4 v[204:207], v252, s[20:21] offset:2048
	v_add_u32_e32 v252, 0x15000, v250
	global_load_dwordx4 v[208:211], v252, s[20:21]
	global_load_dwordx4 v[212:215], v252, s[20:21] offset:2048
	global_load_dwordx4 v[216:219], v[166:167], off offset:528
	global_load_dwordx4 v[150:153], v[166:167], off offset:512
	v_lshlrev_b32_e32 v180, 16, v170
	v_and_b32_e32 v181, 0xffff0000, v170
	v_lshlrev_b32_e32 v170, 16, v171
	v_and_b32_e32 v171, 0xffff0000, v171
	v_lshlrev_b32_e32 v182, 16, v172
	v_and_b32_e32 v183, 0xffff0000, v172
	v_lshlrev_b32_e32 v172, 16, v173
	v_and_b32_e32 v173, 0xffff0000, v173
	v_pk_fma_f32 v[96:97], v[96:97], v[112:113], v[170:171]
	v_pk_fma_f32 v[94:95], v[94:95], v[110:111], v[180:181]
	v_pk_fma_f32 v[170:171], v[92:93], v[104:105], v[172:173]
	v_pk_fma_f32 v[172:173], v[90:91], v[102:103], v[182:183]
	v_cvt_pk_bf16_f32 v90, v94, v95
	v_cvt_pk_bf16_f32 v91, v96, v97
	s_nop 0
	v_cvt_pk_bf16_f32 v92, v172, v173
	v_cvt_pk_bf16_f32 v93, v170, v171
	global_store_dwordx4 v[174:175], v[90:93], off
	s_nop 1
	v_pk_mul_f32 v[90:91], v[172:173], v[172:173]
	v_pk_mul_f32 v[92:93], v[170:171], v[170:171]
	v_pk_fma_f32 v[90:91], v[94:95], v[94:95], v[90:91]
	v_pk_fma_f32 v[92:93], v[96:97], v[96:97], v[92:93]
	v_add_f32_e32 v90, v90, v91
	v_add_f32_e32 v91, v92, v93
	v_add_f32_e32 v90, v90, v91
	v_add_f32_e32 v170, v191, v90
	v_lshlrev_b32_e32 v90, 16, v114
	v_and_b32_e32 v91, 0xffff0000, v114
	v_lshlrev_b32_e32 v94, 16, v116
	v_and_b32_e32 v95, 0xffff0000, v116
	v_pk_fma_f32 v[86:87], v[86:87], v[110:111], v[90:91]
	v_pk_fma_f32 v[90:91], v[82:83], v[102:103], v[94:95]
	v_lshl_add_u64 v[82:83], s[20:21], 0, v[168:169]
	v_lshlrev_b32_e32 v92, 16, v115
	v_and_b32_e32 v93, 0xffff0000, v115
	v_lshlrev_b32_e32 v96, 16, v117
	v_and_b32_e32 v97, 0xffff0000, v117
	v_lshl_add_u64 v[82:83], v[82:83], 0, v[178:179]
	v_pk_fma_f32 v[88:89], v[88:89], v[112:113], v[92:93]
	v_pk_fma_f32 v[84:85], v[84:85], v[104:105], v[96:97]
	v_cvt_pk_bf16_f32 v92, v86, v87
	v_cvt_pk_bf16_f32 v93, v88, v89
	v_cvt_pk_bf16_f32 v94, v90, v91
	v_lshlrev_b32_e32 v96, 16, v109
	v_cvt_pk_bf16_f32 v95, v84, v85
	global_store_dwordx4 v[82:83], v[92:95], off
	v_lshlrev_b32_e32 v82, 16, v106
	v_and_b32_e32 v83, 0xffff0000, v106
	v_pk_fma_f32 v[78:79], v[78:79], v[110:111], v[82:83]
	v_lshl_add_u64 v[82:83], s[20:21], 0, v[140:141]
	v_lshlrev_b32_e32 v92, 16, v107
	v_and_b32_e32 v93, 0xffff0000, v107
	v_lshlrev_b32_e32 v94, 16, v108
	v_and_b32_e32 v95, 0xffff0000, v108
	v_and_b32_e32 v97, 0xffff0000, v109
	v_lshl_add_u64 v[82:83], v[82:83], 0, v[178:179]
	v_pk_fma_f32 v[80:81], v[80:81], v[112:113], v[92:93]
	v_pk_fma_f32 v[76:77], v[76:77], v[104:105], v[96:97]
	v_pk_fma_f32 v[74:75], v[74:75], v[102:103], v[94:95]
	v_cvt_pk_bf16_f32 v92, v78, v79
	v_cvt_pk_bf16_f32 v93, v80, v81
	v_lshlrev_b32_e32 v96, 16, v101
	v_cvt_pk_bf16_f32 v94, v74, v75
	v_cvt_pk_bf16_f32 v95, v76, v77
	global_store_dwordx4 v[82:83], v[92:95], off
	v_lshlrev_b32_e32 v82, 16, v98
	v_and_b32_e32 v83, 0xffff0000, v98
	v_pk_fma_f32 v[70:71], v[70:71], v[110:111], v[82:83]
	v_lshl_add_u64 v[82:83], s[20:21], 0, v[138:139]
	v_lshlrev_b32_e32 v92, 16, v99
	v_and_b32_e32 v93, 0xffff0000, v99
	v_lshlrev_b32_e32 v94, 16, v100
	v_and_b32_e32 v95, 0xffff0000, v100
	v_and_b32_e32 v97, 0xffff0000, v101
	v_lshl_add_u64 v[82:83], v[82:83], 0, v[178:179]
	v_pk_fma_f32 v[72:73], v[72:73], v[112:113], v[92:93]
	v_pk_fma_f32 v[68:69], v[68:69], v[104:105], v[96:97]
	v_pk_fma_f32 v[66:67], v[66:67], v[102:103], v[94:95]
	v_cvt_pk_bf16_f32 v92, v70, v71
	v_cvt_pk_bf16_f32 v93, v72, v73
	s_nop 0
	v_cvt_pk_bf16_f32 v94, v66, v67
	v_cvt_pk_bf16_f32 v95, v68, v69
	global_store_dwordx4 v[82:83], v[92:95], off
	v_and_b32_e32 v83, 64, v232
	v_xor_b32_e32 v82, 16, v232
	v_add_u32_e32 v83, 64, v83
	v_cmp_lt_i32_e32 vcc, v82, v83
	s_nop 1
	v_cndmask_b32_e32 v82, v232, v82, vcc
	v_lshlrev_b32_e32 v92, 2, v82
	v_xor_b32_e32 v82, 32, v232
	v_cmp_lt_i32_e32 vcc, v82, v83
	s_nop 1
	v_cndmask_b32_e32 v82, v232, v82, vcc
	v_lshlrev_b32_e32 v93, 2, v82
	ds_bpermute_b32 v82, v92, v170
	s_waitcnt lgkmcnt(0)
	v_add_f32_e32 v94, v170, v82
	ds_bpermute_b32 v95, v93, v94
	v_lshl_add_u64 v[82:83], v[164:165], 2, s[6:7]
	s_and_saveexec_b64 s[26:27], s[0:1]
	s_mov_b32 s9, 0x44800000
	s_cbranch_execz .LBB0_236
	s_waitcnt lgkmcnt(0)
	v_add_f32_e32 v94, v94, v95
	v_fma_f32 v94, v94, s9, 0.5
	v_cvt_u32_f32_e32 v94, v94
	global_atomic_add v[82:83], v94, off

; __device__ __forceinline__ unsigned cvt_pk_bf16(float lo, float hi) { unsigned r; asm volatile("v_cvt_pk_bf16_f32 %0, %1, %2" : "=v"(r) : "v"(lo), "v"(hi)); return r; }
; #define GAS __attribute__((address_space(1)))
; __device__ __forceinline__ size_t TX(int row, int col) { return ((((size_t)(row >> 8) * 16 + (col >> 6)) * 256 + (row & 255)) << 6) + (col & 63); }
; __device__ __forceinline__ float bf2f(unsigned b) { return __uint_as_float(b << 16); }
;     __device__ __forceinline__ void operator()(const f32x4 (&acc)[2][2][4][2], const pg8::Unit& u, int wr, int wc, int fr, int fq) const {
;     ...
;         for (int ai = 0; ai < 2; ++ai) {
;             float ss[4] = {0.f, 0.f, 0.f, 0.f};
; #pragma unroll
;             for (int bj = 0; bj < 2; ++bj) {
;                 const int col = colb + 128 * bj;
;                 u32x4 xr[4]; f32x4 ga4[2];
; #pragma unroll
;                 for (int m = 0; m < 4; ++m) xr[m] = *(const GAS u32x4*)(xres + TX(row0 + 128 * ai + 16 * m, col));
; #pragma unroll
;                 for (int n = 0; n < 2; ++n) ga4[n] = *(const GAS f32x4*)(ga + col + 4 * n);
; #pragma unroll
;                 for (int m = 0; m < 4; ++m) {
;                     const size_t off = (size_t)(row0 + 128 * ai + 16 * m) * DM + col;
;                     const f32x4 x0 = {bf2f(xr[m].x & 0xffffu), bf2f(xr[m].x >> 16), bf2f(xr[m].y & 0xffffu), bf2f(xr[m].y >> 16)};
;                     const f32x4 x1 = {bf2f(xr[m].z & 0xffffu), bf2f(xr[m].z >> 16), bf2f(xr[m].w & 0xffffu), bf2f(xr[m].w >> 16)};
;                     const f32x4 n0 = x0 + ga4[0] * acc[ai][bj][m][0], n1 = x1 + ga4[1] * acc[ai][bj][m][1];
;                     if (NXT) {
;                         u32x4 w; w.x = cvt_pk_bf16(n0[0], n0[1]); w.y = cvt_pk_bf16(n0[2], n0[3]); w.z = cvt_pk_bf16(n1[0], n1[1]); w.w = cvt_pk_bf16(n1[2], n1[3]);
;                         *(GAS u32x4*)(xres + TX(row0 + 128 * ai + 16 * m, col)) = w;
;                         { const f32x4 q = n0 * n0 + n1 * n1; ss[m] += (q[0] + q[1]) + (q[2] + q[3]); }
.LBB0_242:
	s_or_b64 exec, exec, s[26:27]
	v_add_u32_e32 v68, 0x80, v164
	v_ashrrev_i32_e32 v66, 8, v68
	s_waitcnt lgkmcnt(0)
	v_ashrrev_i32_e32 v67, 31, v66
	v_lshlrev_b64 v[84:85], 12, v[66:67]
	v_and_b32_e32 v95, 0xcf, v68
	v_lshl_add_u64 v[66:67], v[84:85], 0, s[24:25]
	v_or_b32_e32 v68, v66, v95
	v_mov_b32_e32 v69, v67
	v_lshlrev_b64 v[108:109], 7, v[68:69]
	v_lshl_add_u64 v[68:69], v[162:163], 0, v[108:109]
	v_or_b32_e32 v96, 16, v95
	v_or_b32_e32 v68, v66, v96
	v_mov_b32_e32 v69, v67
	v_lshlrev_b64 v[90:91], 7, v[68:69]
	v_lshl_add_u64 v[68:69], v[162:163], 0, v[90:91]
	v_or_b32_e32 v97, 32, v95
	v_or_b32_e32 v98, 48, v95
	v_or_b32_e32 v68, v66, v97
	v_mov_b32_e32 v69, v67
	v_or_b32_e32 v66, v66, v98
	v_lshlrev_b64 v[88:89], 7, v[68:69]
	v_lshlrev_b64 v[86:87], 7, v[66:67]
	v_lshl_add_u64 v[68:69], v[162:163], 0, v[88:89]
	v_lshl_add_u64 v[66:67], v[162:163], 0, v[86:87]
	s_nop 0
	v_lshl_add_u64 v[108:109], s[20:21], 0, v[108:109]
	v_lshl_add_u64 v[108:109], v[108:109], 0, v[178:179]
	s_waitcnt vmcnt(14)
	v_mov_b32_e32 v100, v154
	v_mov_b32_e32 v101, v155
	v_mov_b32_e32 v102, v156
	v_mov_b32_e32 v103, v157
	v_mov_b32_e32 v104, v158
	v_mov_b32_e32 v105, v159
	v_mov_b32_e32 v106, v160
	v_mov_b32_e32 v107, v161
	v_mov_b32_e32 v78, v228
	v_mov_b32_e32 v79, v229
	v_mov_b32_e32 v80, v230
	v_mov_b32_e32 v81, v231
	v_mov_b32_e32 v74, v234
	v_mov_b32_e32 v75, v235
	v_mov_b32_e32 v76, v236
	v_mov_b32_e32 v77, v237
	v_mov_b32_e32 v66, v242
	v_mov_b32_e32 v67, v243
	v_mov_b32_e32 v68, v244
	v_mov_b32_e32 v69, v245
	v_mov_b32_e32 v70, v246
	v_mov_b32_e32 v71, v247
	v_mov_b32_e32 v72, v248
	v_mov_b32_e32 v73, v249
	v_lshlrev_b32_e32 v110, 16, v100
	v_and_b32_e32 v111, 0xffff0000, v100
	v_lshlrev_b32_e32 v100, 16, v101
	v_and_b32_e32 v101, 0xffff0000, v101
	v_lshlrev_b32_e32 v112, 16, v102
	v_and_b32_e32 v113, 0xffff0000, v102
	v_lshlrev_b32_e32 v102, 16, v103
	v_and_b32_e32 v103, 0xffff0000, v103
	v_pk_fma_f32 v[64:65], v[64:65], v[72:73], v[100:101]
	v_pk_fma_f32 v[62:63], v[62:63], v[70:71], v[110:111]
	v_pk_fma_f32 v[100:101], v[60:61], v[68:69], v[102:103]
	v_pk_fma_f32 v[102:103], v[58:59], v[66:67], v[112:113]
	v_cvt_pk_bf16_f32 v58, v62, v63
	v_cvt_pk_bf16_f32 v59, v64, v65
	s_nop 0
	v_cvt_pk_bf16_f32 v60, v102, v103
	v_cvt_pk_bf16_f32 v61, v100, v101
	global_store_dwordx4 v[108:109], v[58:61], off
	s_nop 1
	v_pk_mul_f32 v[58:59], v[102:103], v[102:103]
	v_pk_mul_f32 v[60:61], v[100:101], v[100:101]
	v_pk_fma_f32 v[58:59], v[62:63], v[62:63], v[58:59]
	v_pk_fma_f32 v[60:61], v[64:65], v[64:65], v[60:61]
	v_add_f32_e32 v58, v58, v59
	v_add_f32_e32 v59, v60, v61
	v_lshlrev_b32_e32 v62, 16, v106
	v_and_b32_e32 v63, 0xffff0000, v106
	v_add_f32_e32 v94, v58, v59
	v_lshlrev_b32_e32 v58, 16, v104
	v_and_b32_e32 v59, 0xffff0000, v104
	v_lshlrev_b32_e32 v60, 16, v105
	v_and_b32_e32 v61, 0xffff0000, v105
	v_lshlrev_b32_e32 v64, 16, v107
	v_and_b32_e32 v65, 0xffff0000, v107
	v_pk_fma_f32 v[50:51], v[50:51], v[66:67], v[62:63]
	v_lshl_add_u64 v[62:63], s[20:21], 0, v[90:91]
	v_pk_fma_f32 v[56:57], v[56:57], v[72:73], v[60:61]
	v_pk_fma_f32 v[54:55], v[54:55], v[70:71], v[58:59]
	v_pk_fma_f32 v[52:53], v[52:53], v[68:69], v[64:65]
	v_cvt_pk_bf16_f32 v58, v54, v55
	v_cvt_pk_bf16_f32 v59, v56, v57
	v_cvt_pk_bf16_f32 v60, v50, v51
	v_lshl_add_u64 v[62:63], v[62:63], 0, v[178:179]
	v_cvt_pk_bf16_f32 v61, v52, v53
	global_store_dwordx4 v[62:63], v[58:61], off
	v_lshlrev_b32_e32 v64, 16, v80
	v_and_b32_e32 v65, 0xffff0000, v80
	v_lshlrev_b32_e32 v60, 16, v78
	v_and_b32_e32 v61, 0xffff0000, v78
	v_lshlrev_b32_e32 v58, 16, v79
	v_and_b32_e32 v59, 0xffff0000, v79
	v_pk_fma_f32 v[60:61], v[46:47], v[70:71], v[60:61]
	v_lshl_add_u64 v[46:47], s[20:21], 0, v[88:89]
	v_lshlrev_b32_e32 v62, 16, v81
	v_and_b32_e32 v63, 0xffff0000, v81
	v_pk_fma_f32 v[58:59], v[48:49], v[72:73], v[58:59]
	v_pk_fma_f32 v[64:65], v[42:43], v[66:67], v[64:65]
	v_cvt_pk_bf16_f32 v42, v60, v61
	v_cvt_pk_bf16_f32 v43, v58, v59
	v_lshl_add_u64 v[46:47], v[46:47], 0, v[178:179]
	v_pk_fma_f32 v[62:63], v[44:45], v[68:69], v[62:63]
	v_cvt_pk_bf16_f32 v44, v64, v65
	v_lshlrev_b32_e32 v48, 16, v77
	v_cvt_pk_bf16_f32 v45, v62, v63
	global_store_dwordx4 v[46:47], v[42:45], off
	v_lshlrev_b32_e32 v46, 16, v76
	v_and_b32_e32 v47, 0xffff0000, v76
	v_lshlrev_b32_e32 v42, 16, v74
	v_and_b32_e32 v43, 0xffff0000, v74
	v_lshlrev_b32_e32 v44, 16, v75
	v_and_b32_e32 v45, 0xffff0000, v75
	v_pk_fma_f32 v[70:71], v[38:39], v[70:71], v[42:43]
	v_lshl_add_u64 v[38:39], s[20:21], 0, v[86:87]
	v_and_b32_e32 v49, 0xffff0000, v77
	v_pk_fma_f32 v[72:73], v[40:41], v[72:73], v[44:45]
	v_pk_fma_f32 v[66:67], v[34:35], v[66:67], v[46:47]
	v_cvt_pk_bf16_f32 v34, v70, v71
	v_cvt_pk_bf16_f32 v35, v72, v73
	v_lshl_add_u64 v[38:39], v[38:39], 0, v[178:179]
	v_pk_fma_f32 v[68:69], v[36:37], v[68:69], v[48:49]
	v_cvt_pk_bf16_f32 v36, v66, v67
	s_nop 0
	v_cvt_pk_bf16_f32 v37, v68, v69
	global_store_dwordx4 v[38:39], v[34:37], off
	s_nop 1
	v_lshl_add_u64 v[34:35], v[84:85], 0, v[120:121]
	v_or_b32_e32 v36, v34, v95
	v_mov_b32_e32 v37, v35
	v_lshlrev_b64 v[80:81], 7, v[36:37]
	v_lshl_add_u64 v[36:37], v[162:163], 0, v[80:81]
	v_or_b32_e32 v36, v34, v96
	v_mov_b32_e32 v37, v35
	v_lshlrev_b64 v[78:79], 7, v[36:37]
	v_lshl_add_u64 v[36:37], v[162:163], 0, v[78:79]
	v_or_b32_e32 v36, v34, v97
	v_mov_b32_e32 v37, v35
	v_or_b32_e32 v34, v34, v98
	v_lshlrev_b64 v[76:77], 7, v[36:37]
	v_lshlrev_b64 v[74:75], 7, v[34:35]
	v_lshl_add_u64 v[36:37], v[162:163], 0, v[76:77]
	v_lshl_add_u64 v[34:35], v[162:163], 0, v[74:75]
	s_nop 0
	v_lshl_add_u64 v[80:81], s[20:21], 0, v[80:81]
	v_lshl_add_u64 v[80:81], v[80:81], 0, v[178:179]
	s_waitcnt vmcnt(8)
; __device__ __forceinline__ unsigned cvt_pk_bf16(float lo, float hi) { unsigned r; asm volatile("v_cvt_pk_bf16_f32 %0, %1, %2" : "=v"(r) : "v"(lo), "v"(hi)); return r; }
; #define GAS __attribute__((address_space(1)))
; __device__ __forceinline__ size_t TX(int row, int col) { return ((((size_t)(row >> 8) * 16 + (col >> 6)) * 256 + (row & 255)) << 6) + (col & 63); }
; __device__ __forceinline__ float bf2f(unsigned b) { return __uint_as_float(b << 16); }
;     __device__ __forceinline__ void operator()(const f32x4 (&acc)[2][2][4][2], const pg8::Unit& u, int wr, int wc, int fr, int fq) const {
;     ...
;                 for (int m = 0; m < 4; ++m) {
;                     const size_t off = (size_t)(row0 + 128 * ai + 16 * m) * DM + col;
;                     const f32x4 x0 = {bf2f(xr[m].x & 0xffffu), bf2f(xr[m].x >> 16), bf2f(xr[m].y & 0xffffu), bf2f(xr[m].y >> 16)};
;                     const f32x4 x1 = {bf2f(xr[m].z & 0xffffu), bf2f(xr[m].z >> 16), bf2f(xr[m].w & 0xffffu), bf2f(xr[m].w >> 16)};
;                     const f32x4 n0 = x0 + ga4[0] * acc[ai][bj][m][0], n1 = x1 + ga4[1] * acc[ai][bj][m][1];
;                     if (NXT) {
;                         u32x4 w; w.x = cvt_pk_bf16(n0[0], n0[1]); w.y = cvt_pk_bf16(n0[2], n0[3]); w.z = cvt_pk_bf16(n1[0], n1[1]); w.w = cvt_pk_bf16(n1[2], n1[3]);
;                         *(GAS u32x4*)(xres + TX(row0 + 128 * ai + 16 * m, col)) = w;
;                         { const f32x4 q = n0 * n0 + n1 * n1; ss[m] += (q[0] + q[1]) + (q[2] + q[3]); }
;                     } else { *(GAS f32x4*)(fout + off) = n0; *(GAS f32x4*)(fout + off + 4) = n1; }
;                 }
;             }
;             if (NXT) {
; #pragma unroll
;                 for (int m = 0; m < 4; ++m) { float s = ss[m]; s += __shfl_xor(s, 16); s += __shfl_xor(s, 32);
;                     if (fq == 0) __hip_atomic_fetch_add(ssq_out + row0 + 128 * ai + 16 * m, (unsigned)(s * 1024.0f + 0.5f), __ATOMIC_RELAXED, __HIP_MEMORY_SCOPE_AGENT); }
	v_mov_b32_e32 v84, v200
	v_mov_b32_e32 v85, v201
	v_mov_b32_e32 v86, v202
	v_mov_b32_e32 v87, v203
	v_mov_b32_e32 v88, v204
	v_mov_b32_e32 v89, v205
	v_mov_b32_e32 v90, v206
	v_mov_b32_e32 v91, v207
	v_mov_b32_e32 v42, v208
	v_mov_b32_e32 v43, v209
	v_mov_b32_e32 v44, v210
	v_mov_b32_e32 v45, v211
	v_mov_b32_e32 v38, v212
	v_mov_b32_e32 v39, v213
	v_mov_b32_e32 v40, v214
	v_mov_b32_e32 v41, v215
	v_mov_b32_e32 v34, v216
	v_mov_b32_e32 v35, v217
	v_mov_b32_e32 v36, v218
	v_mov_b32_e32 v37, v219
	v_mov_b32_e32 v46, v150
	v_mov_b32_e32 v47, v151
	v_mov_b32_e32 v48, v152
	v_mov_b32_e32 v49, v153
	v_lshlrev_b32_e32 v96, 16, v84
	v_and_b32_e32 v97, 0xffff0000, v84
	v_lshlrev_b32_e32 v84, 16, v85
	v_and_b32_e32 v85, 0xffff0000, v85
	v_lshlrev_b32_e32 v98, 16, v86
	v_and_b32_e32 v99, 0xffff0000, v86
	v_lshlrev_b32_e32 v86, 16, v87
	v_and_b32_e32 v87, 0xffff0000, v87
	v_pk_fma_f32 v[32:33], v[32:33], v[48:49], v[84:85]
	v_pk_fma_f32 v[30:31], v[30:31], v[46:47], v[96:97]
	v_pk_fma_f32 v[84:85], v[28:29], v[36:37], v[86:87]
	v_pk_fma_f32 v[86:87], v[26:27], v[34:35], v[98:99]
	v_cvt_pk_bf16_f32 v26, v30, v31
	v_cvt_pk_bf16_f32 v27, v32, v33
	s_nop 0
	v_cvt_pk_bf16_f32 v28, v86, v87
	v_cvt_pk_bf16_f32 v29, v84, v85
	global_store_dwordx4 v[80:81], v[26:29], off
	s_nop 1
	v_pk_mul_f32 v[26:27], v[86:87], v[86:87]
	v_pk_mul_f32 v[28:29], v[84:85], v[84:85]
	v_pk_fma_f32 v[26:27], v[30:31], v[30:31], v[26:27]
	v_pk_fma_f32 v[28:29], v[32:33], v[32:33], v[28:29]
	v_add_f32_e32 v26, v26, v27
	v_add_f32_e32 v27, v28, v29
	v_lshlrev_b32_e32 v28, 16, v89
	v_and_b32_e32 v29, 0xffff0000, v89
	v_lshlrev_b32_e32 v30, 16, v90
	v_and_b32_e32 v31, 0xffff0000, v90
	v_add_f32_e32 v26, v26, v27
	v_pk_fma_f32 v[24:25], v[24:25], v[48:49], v[28:29]
	v_pk_fma_f32 v[28:29], v[18:19], v[34:35], v[30:31]
	v_lshl_add_u64 v[30:31], s[20:21], 0, v[78:79]
	v_add_f32_e32 v80, v94, v26
	v_lshlrev_b32_e32 v26, 16, v88
	v_and_b32_e32 v27, 0xffff0000, v88
	v_lshlrev_b32_e32 v32, 16, v91
	v_and_b32_e32 v33, 0xffff0000, v91
	v_lshl_add_u64 v[30:31], v[30:31], 0, v[178:179]
	v_pk_fma_f32 v[22:23], v[22:23], v[46:47], v[26:27]
	v_pk_fma_f32 v[26:27], v[20:21], v[36:37], v[32:33]
	v_cvt_pk_bf16_f32 v18, v22, v23
	v_cvt_pk_bf16_f32 v19, v24, v25
	v_cvt_pk_bf16_f32 v20, v28, v29
	v_lshlrev_b32_e32 v32, 16, v45
	v_cvt_pk_bf16_f32 v21, v26, v27
	global_store_dwordx4 v[30:31], v[18:21], off
	v_lshlrev_b32_e32 v30, 16, v44
	v_and_b32_e32 v31, 0xffff0000, v44
	v_pk_fma_f32 v[10:11], v[10:11], v[34:35], v[30:31]
	v_lshl_add_u64 v[30:31], s[20:21], 0, v[76:77]
	v_lshlrev_b32_e32 v18, 16, v42
	v_and_b32_e32 v19, 0xffff0000, v42
	v_lshlrev_b32_e32 v20, 16, v43
	v_and_b32_e32 v21, 0xffff0000, v43
	v_and_b32_e32 v33, 0xffff0000, v45
	v_lshl_add_u64 v[30:31], v[30:31], 0, v[178:179]
	v_pk_fma_f32 v[16:17], v[16:17], v[48:49], v[20:21]
	v_pk_fma_f32 v[14:15], v[14:15], v[46:47], v[18:19]
	v_pk_fma_f32 v[12:13], v[12:13], v[36:37], v[32:33]
	v_cvt_pk_bf16_f32 v18, v14, v15
	v_cvt_pk_bf16_f32 v19, v16, v17
	v_cvt_pk_bf16_f32 v20, v10, v11
	v_lshlrev_b32_e32 v32, 16, v41
	v_cvt_pk_bf16_f32 v21, v12, v13
	global_store_dwordx4 v[30:31], v[18:21], off
	v_lshlrev_b32_e32 v30, 16, v40
	v_and_b32_e32 v31, 0xffff0000, v40
	v_lshlrev_b32_e32 v18, 16, v38
	v_and_b32_e32 v19, 0xffff0000, v38
	v_pk_fma_f32 v[2:3], v[2:3], v[34:35], v[30:31]
	v_lshl_add_u64 v[30:31], s[20:21], 0, v[74:75]
	v_lshlrev_b32_e32 v20, 16, v39
	v_and_b32_e32 v21, 0xffff0000, v39
	v_and_b32_e32 v33, 0xffff0000, v41
	v_pk_fma_f32 v[6:7], v[6:7], v[46:47], v[18:19]
	v_lshl_add_u64 v[30:31], v[30:31], 0, v[178:179]
	v_cvt_pk_bf16_f32 v18, v6, v7
	v_pk_fma_f32 v[8:9], v[8:9], v[48:49], v[20:21]
	v_pk_fma_f32 v[4:5], v[4:5], v[36:37], v[32:33]
	v_cvt_pk_bf16_f32 v19, v8, v9
	v_cvt_pk_bf16_f32 v20, v2, v3
	s_nop 0
	v_cvt_pk_bf16_f32 v21, v4, v5
	global_store_dwordx4 v[30:31], v[18:21], off
	ds_bpermute_b32 v18, v92, v80
	s_waitcnt lgkmcnt(0)
	v_add_f32_e32 v18, v80, v18
	ds_bpermute_b32 v19, v93, v18
	s_and_saveexec_b64 s[24:25], s[0:1]
	s_cbranch_execz .LBB0_244
	s_waitcnt lgkmcnt(0)
	v_add_f32_e32 v18, v18, v19
	v_fma_f32 v18, v18, s9, 0.5
	v_cvt_u32_f32_e32 v18, v18
	global_atomic_add v[82:83], v18, off offset:512

; __device__ __forceinline__ unsigned cvt_pk_bf16(float lo, float hi) { unsigned r; asm volatile("v_cvt_pk_bf16_f32 %0, %1, %2" : "=v"(r) : "v"(lo), "v"(hi)); return r; }
; #define GAS __attribute__((address_space(1)))
; __device__ __forceinline__ size_t TX(int row, int col) { return ((((size_t)(row >> 8) * 16 + (col >> 6)) * 256 + (row & 255)) << 6) + (col & 63); }
; __device__ __forceinline__ float bf2f(unsigned b) { return __uint_as_float(b << 16); }
;     __device__ __forceinline__ void operator()(const f32x4 (&acc)[2][2][4][2], const pg8::Unit& u, int wr, int wc, int fr, int fq) const {
;         const int colb = 256 * u.pn + 32 * wc + 8 * fq, row0 = 256 * u.pm + 64 * wr + fr;
; #pragma unroll
;         for (int ai = 0; ai < 2; ++ai) {
;             float ss[4] = {0.f, 0.f, 0.f, 0.f};
; #pragma unroll
;             for (int bj = 0; bj < 2; ++bj) {
;                 const int col = colb + 128 * bj;
;                 u32x4 xr[4]; f32x4 ga4[2];
; #pragma unroll
;                 for (int m = 0; m < 4; ++m) xr[m] = *(const GAS u32x4*)(xres + TX(row0 + 128 * ai + 16 * m, col));
; #pragma unroll
;                 for (int n = 0; n < 2; ++n) ga4[n] = *(const GAS f32x4*)(ga + col + 4 * n);
; #pragma unroll
;                 for (int m = 0; m < 4; ++m) {
;                     const size_t off = (size_t)(row0 + 128 * ai + 16 * m) * DM + col;
;                     const f32x4 x0 = {bf2f(xr[m].x & 0xffffu), bf2f(xr[m].x >> 16), bf2f(xr[m].y & 0xffffu), bf2f(xr[m].y >> 16)};
;                     const f32x4 x1 = {bf2f(xr[m].z & 0xffffu), bf2f(xr[m].z >> 16), bf2f(xr[m].w & 0xffffu), bf2f(xr[m].w >> 16)};
;                     const f32x4 n0 = x0 + ga4[0] * acc[ai][bj][m][0], n1 = x1 + ga4[1] * acc[ai][bj][m][1];
;                     if (NXT) {
;                         u32x4 w; w.x = cvt_pk_bf16(n0[0], n0[1]); w.y = cvt_pk_bf16(n0[2], n0[3]); w.z = cvt_pk_bf16(n1[0], n1[1]); w.w = cvt_pk_bf16(n1[2], n1[3]);
;                         *(GAS u32x4*)(xres + TX(row0 + 128 * ai + 16 * m, col)) = w;
;                         { const f32x4 q = n0 * n0 + n1 * n1; ss[m] += (q[0] + q[1]) + (q[2] + q[3]); }
.LBB0_481:
	s_lshl_b32 s16, s66, 8
	s_or_b32 s24, s16, s57
	s_lshl_b32 s16, s65, 8
	s_add_i32 s25, s16, s30
	s_ashr_i32 s16, s25, 8
	s_ashr_i32 s17, s16, 31
	s_lshl_b64 s[18:19], s[16:17], 12
	s_ashr_i32 s16, s24, 6
	s_ashr_i32 s17, s16, 31
	s_lshl_b64 s[16:17], s[16:17], 8
	v_or_b32_e32 v168, s24, v176
	v_bitop3_b32 v130, s24, 56, v176 bitop3:0xc8
	s_add_u32 s24, s18, s16
	v_or_b32_e32 v164, s25, v1
	v_bitop3_b32 v186, s25, v224, v1 bitop3:0xc8
	s_addc_u32 s25, s19, s17
	v_lshlrev_b32_e32 v178, 1, v130
	v_or_b32_e32 v130, s24, v186
	v_mov_b32_e32 v131, s25
	v_or_b32_e32 v189, 16, v186
	v_lshlrev_b64 v[190:191], 7, v[130:131]
	v_or_b32_e32 v130, s24, v189
	v_or_b32_e32 v187, 32, v186
	v_lshl_add_u64 v[162:163], s[20:21], 0, v[178:179]
	v_lshlrev_b64 v[174:175], 7, v[130:131]
	v_or_b32_e32 v130, s24, v187
	v_or_b32_e32 v188, 48, v186
	v_lshl_add_u64 v[132:133], v[162:163], 0, v[190:191]
	v_lshlrev_b64 v[172:173], 7, v[130:131]
	v_or_b32_e32 v130, s24, v188
	global_load_dwordx4 v[180:183], v[132:133], off
	v_subrev_u32_e32 v250, s20, v132
	v_lshl_add_u64 v[132:133], v[162:163], 0, v[174:175]
	v_lshlrev_b64 v[170:171], 7, v[130:131]
	v_ashrrev_i32_e32 v169, 31, v168
	global_load_dwordx4 v[146:149], v[132:133], off
	v_lshl_add_u64 v[132:133], v[162:163], 0, v[172:173]
	v_lshl_add_u64 v[130:131], v[162:163], 0, v[170:171]
	v_lshl_add_u64 v[166:167], v[168:169], 2, s[6:7]
	global_load_dwordx4 v[142:145], v[132:133], off
	v_lshl_add_u64 v[190:191], s[20:21], 0, v[190:191]
	global_load_dwordx4 v[130:133], v[130:131], off
	s_nop 0
	global_load_dwordx4 v[134:137], v[166:167], off offset:16
	global_load_dwordx4 v[138:141], v[166:167], off
	v_add_u32_e32 v252, 0x10000, v250
	global_load_dwordx4 v[200:203], v252, s[20:21]
	global_load_dwordx4 v[204:207], v252, s[20:21] offset:2048
	v_add_u32_e32 v252, 0x11000, v250
	global_load_dwordx4 v[208:211], v252, s[20:21]
	global_load_dwordx4 v[212:215], v252, s[20:21] offset:2048
	global_load_dwordx4 v[216:219], v[166:167], off offset:528
	global_load_dwordx4 v[150:153], v[166:167], off offset:512
	v_add_u32_e32 v252, 0x4000, v250
	global_load_dwordx4 v[154:157], v252, s[20:21]
	global_load_dwordx4 v[158:161], v252, s[20:21] offset:2048
	v_add_u32_e32 v252, 0x5000, v250
	global_load_dwordx4 v[228:231], v252, s[20:21]
	global_load_dwordx4 v[234:237], v252, s[20:21] offset:2048
	global_load_dwordx4 v[242:245], v[166:167], off offset:16
	global_load_dwordx4 v[246:249], v[166:167], off
	v_lshl_add_u64 v[190:191], v[190:191], 0, v[178:179]
	v_ashrrev_i32_e32 v165, 31, v164
	s_waitcnt vmcnt(12)
	v_lshlrev_b32_e32 v192, 16, v180
	v_and_b32_e32 v193, 0xffff0000, v180
	v_lshlrev_b32_e32 v180, 16, v181
	v_and_b32_e32 v181, 0xffff0000, v181
	v_lshlrev_b32_e32 v196, 16, v182
	v_and_b32_e32 v197, 0xffff0000, v182
	v_lshlrev_b32_e32 v182, 16, v183
	v_and_b32_e32 v183, 0xffff0000, v183
	v_pk_fma_f32 v[128:129], v[128:129], v[140:141], v[180:181]
	v_pk_fma_f32 v[126:127], v[126:127], v[138:139], v[192:193]
	v_pk_fma_f32 v[180:181], v[124:125], v[136:137], v[182:183]
	v_pk_fma_f32 v[182:183], v[122:123], v[134:135], v[196:197]
	v_cvt_pk_bf16_f32 v122, v126, v127
	v_cvt_pk_bf16_f32 v123, v128, v129
	s_nop 0
	v_cvt_pk_bf16_f32 v124, v182, v183
	v_cvt_pk_bf16_f32 v125, v180, v181
	global_store_dwordx4 v[190:191], v[122:125], off
	s_nop 1
	v_pk_mul_f32 v[122:123], v[182:183], v[182:183]
	v_pk_mul_f32 v[124:125], v[180:181], v[180:181]
	v_pk_fma_f32 v[122:123], v[126:127], v[126:127], v[122:123]
	v_pk_fma_f32 v[124:125], v[128:129], v[128:129], v[124:125]
	v_add_f32_e32 v122, v122, v123
	v_add_f32_e32 v123, v124, v125
	v_lshlrev_b32_e32 v124, 16, v146
	v_and_b32_e32 v125, 0xffff0000, v146
	v_add_f32_e32 v190, v122, v123
	v_lshlrev_b32_e32 v122, 16, v147
	v_and_b32_e32 v123, 0xffff0000, v147
	v_lshlrev_b32_e32 v128, 16, v148
	v_and_b32_e32 v129, 0xffff0000, v148
	v_pk_fma_f32 v[124:125], v[118:119], v[138:139], v[124:125]
	v_lshl_add_u64 v[118:119], s[20:21], 0, v[174:175]
	v_lshlrev_b32_e32 v126, 16, v149
	v_and_b32_e32 v127, 0xffff0000, v149
	v_pk_fma_f32 v[122:123], v[120:121], v[140:141], v[122:123]
	v_pk_fma_f32 v[128:129], v[114:115], v[134:135], v[128:129]
	v_cvt_pk_bf16_f32 v114, v124, v125
	v_cvt_pk_bf16_f32 v115, v122, v123
	v_lshl_add_u64 v[118:119], v[118:119], 0, v[178:179]
	v_pk_fma_f32 v[126:127], v[116:117], v[136:137], v[126:127]
	v_cvt_pk_bf16_f32 v116, v128, v129
	v_lshlrev_b32_e32 v120, 16, v145
	v_cvt_pk_bf16_f32 v117, v126, v127
	global_store_dwordx4 v[118:119], v[114:117], off
	v_lshlrev_b32_e32 v118, 16, v144
	v_and_b32_e32 v119, 0xffff0000, v144
	v_lshlrev_b32_e32 v114, 16, v142
	v_and_b32_e32 v115, 0xffff0000, v142
	v_lshlrev_b32_e32 v116, 16, v143
	v_and_b32_e32 v117, 0xffff0000, v143
	v_and_b32_e32 v121, 0xffff0000, v145
	v_pk_fma_f32 v[144:145], v[110:111], v[138:139], v[114:115]
	v_lshl_add_u64 v[110:111], s[20:21], 0, v[172:173]
	v_pk_fma_f32 v[142:143], v[112:113], v[140:141], v[116:117]
	v_pk_fma_f32 v[148:149], v[106:107], v[134:135], v[118:119]
	v_cvt_pk_bf16_f32 v106, v144, v145
	v_cvt_pk_bf16_f32 v107, v142, v143
	v_lshl_add_u64 v[110:111], v[110:111], 0, v[178:179]
	v_pk_fma_f32 v[146:147], v[108:109], v[136:137], v[120:121]
	v_cvt_pk_bf16_f32 v108, v148, v149
	v_lshlrev_b32_e32 v112, 16, v133
	v_cvt_pk_bf16_f32 v109, v146, v147
	global_store_dwordx4 v[110:111], v[106:109], off
	v_lshlrev_b32_e32 v110, 16, v132
	v_and_b32_e32 v111, 0xffff0000, v132
	v_lshlrev_b32_e32 v106, 16, v130
	v_and_b32_e32 v107, 0xffff0000, v130
	v_and_b32_e32 v113, 0xffff0000, v133
	v_pk_fma_f32 v[132:133], v[102:103], v[138:139], v[106:107]
	v_lshl_add_u64 v[102:103], s[20:21], 0, v[170:171]
	v_lshlrev_b32_e32 v108, 16, v131
; __device__ __forceinline__ unsigned cvt_pk_bf16(float lo, float hi) { unsigned r; asm volatile("v_cvt_pk_bf16_f32 %0, %1, %2" : "=v"(r) : "v"(lo), "v"(hi)); return r; }
; #define GAS __attribute__((address_space(1)))
; __device__ __forceinline__ size_t TX(int row, int col) { return ((((size_t)(row >> 8) * 16 + (col >> 6)) * 256 + (row & 255)) << 6) + (col & 63); }
; __device__ __forceinline__ float bf2f(unsigned b) { return __uint_as_float(b << 16); }
;     __device__ __forceinline__ void operator()(const f32x4 (&acc)[2][2][4][2], const pg8::Unit& u, int wr, int wc, int fr, int fq) const {
;     ...
;                 for (int m = 0; m < 4; ++m) xr[m] = *(const GAS u32x4*)(xres + TX(row0 + 128 * ai + 16 * m, col));
; #pragma unroll
;                 for (int n = 0; n < 2; ++n) ga4[n] = *(const GAS f32x4*)(ga + col + 4 * n);
; #pragma unroll
;                 for (int m = 0; m < 4; ++m) {
;                     const size_t off = (size_t)(row0 + 128 * ai + 16 * m) * DM + col;
;                     const f32x4 x0 = {bf2f(xr[m].x & 0xffffu), bf2f(xr[m].x >> 16), bf2f(xr[m].y & 0xffffu), bf2f(xr[m].y >> 16)};
;                     const f32x4 x1 = {bf2f(xr[m].z & 0xffffu), bf2f(xr[m].z >> 16), bf2f(xr[m].w & 0xffffu), bf2f(xr[m].w >> 16)};
;                     const f32x4 n0 = x0 + ga4[0] * acc[ai][bj][m][0], n1 = x1 + ga4[1] * acc[ai][bj][m][1];
;                     if (NXT) {
;                         u32x4 w; w.x = cvt_pk_bf16(n0[0], n0[1]); w.y = cvt_pk_bf16(n0[2], n0[3]); w.z = cvt_pk_bf16(n1[0], n1[1]); w.w = cvt_pk_bf16(n1[2], n1[3]);
;                         *(GAS u32x4*)(xres + TX(row0 + 128 * ai + 16 * m, col)) = w;
;                         { const f32x4 q = n0 * n0 + n1 * n1; ss[m] += (q[0] + q[1]) + (q[2] + q[3]); }
;                     } else { *(GAS f32x4*)(fout + off) = n0; *(GAS f32x4*)(fout + off + 4) = n1; }
;                 }
;             }
;             if (NXT) {
; #pragma unroll
;                 for (int m = 0; m < 4; ++m) { float s = ss[m]; s += __shfl_xor(s, 16); s += __shfl_xor(s, 32);
;                     if (fq == 0) __hip_atomic_fetch_add(ssq_out + row0 + 128 * ai + 16 * m, (unsigned)(s * 1024.0f + 0.5f), __ATOMIC_RELAXED, __HIP_MEMORY_SCOPE_AGENT); }
	v_and_b32_e32 v109, 0xffff0000, v131
	v_lshl_add_u64 v[102:103], v[102:103], 0, v[178:179]
	v_pk_fma_f32 v[130:131], v[104:105], v[140:141], v[108:109]
	v_pk_fma_f32 v[136:137], v[100:101], v[136:137], v[112:113]
	v_pk_fma_f32 v[134:135], v[98:99], v[134:135], v[110:111]
	v_cvt_pk_bf16_f32 v98, v132, v133
	v_cvt_pk_bf16_f32 v99, v130, v131
	s_nop 0
	v_cvt_pk_bf16_f32 v100, v134, v135
	v_cvt_pk_bf16_f32 v101, v136, v137
	global_store_dwordx4 v[102:103], v[98:101], off
	v_or_b32_e32 v102, 0x80, v168
	v_ashrrev_i32_e32 v103, 31, v102
	v_ashrrev_i32_e32 v98, 6, v102
	v_ashrrev_i32_e32 v99, 31, v98
	v_lshlrev_b64 v[120:121], 8, v[98:99]
	v_lshl_add_u64 v[98:99], v[120:121], 0, s[18:19]
	v_or_b32_e32 v100, v98, v186
	v_mov_b32_e32 v101, v99
	v_lshlrev_b64 v[174:175], 7, v[100:101]
	v_lshl_add_u64 v[100:101], v[162:163], 0, v[174:175]
	v_or_b32_e32 v100, v98, v189
	v_mov_b32_e32 v101, v99
	v_lshlrev_b64 v[168:169], 7, v[100:101]
	v_lshl_add_u64 v[100:101], v[162:163], 0, v[168:169]
	v_or_b32_e32 v100, v98, v187
	v_mov_b32_e32 v101, v99
	v_or_b32_e32 v98, v98, v188
	v_lshlrev_b64 v[140:141], 7, v[100:101]
	v_lshlrev_b64 v[138:139], 7, v[98:99]
	v_lshl_add_u64 v[100:101], v[162:163], 0, v[140:141]
	v_lshl_add_u64 v[98:99], v[162:163], 0, v[138:139]
	v_lshl_add_u64 v[118:119], v[102:103], 2, s[6:7]
	v_lshl_add_u64 v[174:175], s[20:21], 0, v[174:175]
	s_nop 0
	v_lshl_add_u64 v[174:175], v[174:175], 0, v[178:179]
	s_waitcnt vmcnt(10)
	v_mov_b32_e32 v170, v200
	v_mov_b32_e32 v171, v201
	v_mov_b32_e32 v172, v202
	v_mov_b32_e32 v173, v203
	v_mov_b32_e32 v114, v204
	v_mov_b32_e32 v115, v205
	v_mov_b32_e32 v116, v206
	v_mov_b32_e32 v117, v207
	v_mov_b32_e32 v106, v208
	v_mov_b32_e32 v107, v209
	v_mov_b32_e32 v108, v210
	v_mov_b32_e32 v109, v211
	v_mov_b32_e32 v98, v212
	v_mov_b32_e32 v99, v213
	v_mov_b32_e32 v100, v214
	v_mov_b32_e32 v101, v215
	v_mov_b32_e32 v102, v216
	v_mov_b32_e32 v103, v217
	v_mov_b32_e32 v104, v218
	v_mov_b32_e32 v105, v219
	v_mov_b32_e32 v110, v150
	v_mov_b32_e32 v111, v151
	v_mov_b32_e32 v112, v152
	v_mov_b32_e32 v113, v153
	v_add_u32_e32 v252, 0x14000, v250
	global_load_dwordx4 v[200:203], v252, s[20:21]
	global_load_dwordx4 v[204:207], v252, s[20:21] offset:2048
	v_add_u32_e32 v252, 0x15000, v250
	global_load_dwordx4 v[208:211], v252, s[20:21]
	global_load_dwordx4 v[212:215], v252, s[20:21] offset:2048
	global_load_dwordx4 v[216:219], v[166:167], off offset:528
	global_load_dwordx4 v[150:153], v[166:167], off offset:512
	v_lshlrev_b32_e32 v180, 16, v170
	v_and_b32_e32 v181, 0xffff0000, v170
	v_lshlrev_b32_e32 v170, 16, v171
	v_and_b32_e32 v171, 0xffff0000, v171
	v_lshlrev_b32_e32 v182, 16, v172
	v_and_b32_e32 v183, 0xffff0000, v172
	v_lshlrev_b32_e32 v172, 16, v173
	v_and_b32_e32 v173, 0xffff0000, v173
	v_pk_fma_f32 v[96:97], v[96:97], v[112:113], v[170:171]
	v_pk_fma_f32 v[94:95], v[94:95], v[110:111], v[180:181]
	v_pk_fma_f32 v[170:171], v[92:93], v[104:105], v[172:173]
	v_pk_fma_f32 v[172:173], v[90:91], v[102:103], v[182:183]
	v_cvt_pk_bf16_f32 v90, v94, v95
	v_cvt_pk_bf16_f32 v91, v96, v97
	s_nop 0
	v_cvt_pk_bf16_f32 v92, v172, v173
	v_cvt_pk_bf16_f32 v93, v170, v171
	global_store_dwordx4 v[174:175], v[90:93], off
	s_nop 1
	v_pk_mul_f32 v[90:91], v[172:173], v[172:173]
	v_pk_mul_f32 v[92:93], v[170:171], v[170:171]
	v_pk_fma_f32 v[90:91], v[94:95], v[94:95], v[90:91]
	v_pk_fma_f32 v[92:93], v[96:97], v[96:97], v[92:93]
	v_add_f32_e32 v90, v90, v91
	v_add_f32_e32 v91, v92, v93
	v_add_f32_e32 v90, v90, v91
	v_add_f32_e32 v170, v190, v90
	v_lshlrev_b32_e32 v90, 16, v114
	v_and_b32_e32 v91, 0xffff0000, v114
	v_lshlrev_b32_e32 v94, 16, v116
	v_and_b32_e32 v95, 0xffff0000, v116
	v_pk_fma_f32 v[86:87], v[86:87], v[110:111], v[90:91]
	v_pk_fma_f32 v[90:91], v[82:83], v[102:103], v[94:95]
	v_lshl_add_u64 v[82:83], s[20:21], 0, v[168:169]
	v_lshlrev_b32_e32 v92, 16, v115
	v_and_b32_e32 v93, 0xffff0000, v115
	v_lshlrev_b32_e32 v96, 16, v117
	v_and_b32_e32 v97, 0xffff0000, v117
	v_lshl_add_u64 v[82:83], v[82:83], 0, v[178:179]
	v_pk_fma_f32 v[88:89], v[88:89], v[112:113], v[92:93]
	v_pk_fma_f32 v[84:85], v[84:85], v[104:105], v[96:97]
	v_cvt_pk_bf16_f32 v92, v86, v87
	v_cvt_pk_bf16_f32 v93, v88, v89
	v_cvt_pk_bf16_f32 v94, v90, v91
	v_lshlrev_b32_e32 v96, 16, v109
	v_cvt_pk_bf16_f32 v95, v84, v85
	global_store_dwordx4 v[82:83], v[92:95], off
	v_lshlrev_b32_e32 v82, 16, v106
	v_and_b32_e32 v83, 0xffff0000, v106
	v_pk_fma_f32 v[78:79], v[78:79], v[110:111], v[82:83]
	v_lshl_add_u64 v[82:83], s[20:21], 0, v[140:141]
	v_lshlrev_b32_e32 v92, 16, v107
	v_and_b32_e32 v93, 0xffff0000, v107
	v_lshlrev_b32_e32 v94, 16, v108
	v_and_b32_e32 v95, 0xffff0000, v108
	v_and_b32_e32 v97, 0xffff0000, v109
	v_lshl_add_u64 v[82:83], v[82:83], 0, v[178:179]
	v_pk_fma_f32 v[80:81], v[80:81], v[112:113], v[92:93]
	v_pk_fma_f32 v[76:77], v[76:77], v[104:105], v[96:97]
	v_pk_fma_f32 v[74:75], v[74:75], v[102:103], v[94:95]
	v_cvt_pk_bf16_f32 v92, v78, v79
	v_cvt_pk_bf16_f32 v93, v80, v81
	v_lshlrev_b32_e32 v96, 16, v101
	v_cvt_pk_bf16_f32 v94, v74, v75
	v_cvt_pk_bf16_f32 v95, v76, v77
	global_store_dwordx4 v[82:83], v[92:95], off
	v_lshlrev_b32_e32 v82, 16, v98
	v_and_b32_e32 v83, 0xffff0000, v98
	v_pk_fma_f32 v[70:71], v[70:71], v[110:111], v[82:83]
	v_lshl_add_u64 v[82:83], s[20:21], 0, v[138:139]
	v_lshlrev_b32_e32 v92, 16, v99
	v_and_b32_e32 v93, 0xffff0000, v99
	v_lshlrev_b32_e32 v94, 16, v100
	v_and_b32_e32 v95, 0xffff0000, v100
	v_and_b32_e32 v97, 0xffff0000, v101
	v_lshl_add_u64 v[82:83], v[82:83], 0, v[178:179]
	v_pk_fma_f32 v[72:73], v[72:73], v[112:113], v[92:93]
	v_pk_fma_f32 v[68:69], v[68:69], v[104:105], v[96:97]
	v_pk_fma_f32 v[66:67], v[66:67], v[102:103], v[94:95]
	v_cvt_pk_bf16_f32 v92, v70, v71
	v_cvt_pk_bf16_f32 v93, v72, v73
	s_nop 0
	v_cvt_pk_bf16_f32 v94, v66, v67
	v_cvt_pk_bf16_f32 v95, v68, v69
	global_store_dwordx4 v[82:83], v[92:95], off
	v_and_b32_e32 v83, 64, v232
	v_xor_b32_e32 v82, 16, v232
	v_add_u32_e32 v83, 64, v83
	v_cmp_lt_i32_e32 vcc, v82, v83
	s_nop 1
	v_cndmask_b32_e32 v82, v232, v82, vcc
	v_lshlrev_b32_e32 v92, 2, v82
	v_xor_b32_e32 v82, 32, v232
	v_cmp_lt_i32_e32 vcc, v82, v83
	s_nop 1
	v_cndmask_b32_e32 v82, v232, v82, vcc
	v_lshlrev_b32_e32 v93, 2, v82
	ds_bpermute_b32 v82, v92, v170
	s_waitcnt lgkmcnt(0)
	v_add_f32_e32 v94, v170, v82
	ds_bpermute_b32 v95, v93, v94
	v_lshl_add_u64 v[82:83], v[164:165], 2, s[10:11]
	s_and_saveexec_b64 s[18:19], s[0:1]
	s_mov_b32 s69, 0x2aaaaaab
	s_mov_b32 s72, 0x44800000
	s_movk_i32 s68, 0x6000
	s_mov_b32 s67, 0xc000
	s_cbranch_execz .LBB0_483
	s_waitcnt lgkmcnt(0)
	v_add_f32_e32 v94, v94, v95
	v_fma_f32 v94, v94, s72, 0.5
	v_cvt_u32_f32_e32 v94, v94
	global_atomic_add v[82:83], v94, off

; __device__ __forceinline__ unsigned cvt_pk_bf16(float lo, float hi) { unsigned r; asm volatile("v_cvt_pk_bf16_f32 %0, %1, %2" : "=v"(r) : "v"(lo), "v"(hi)); return r; }
; #define GAS __attribute__((address_space(1)))
; __device__ __forceinline__ size_t TX(int row, int col) { return ((((size_t)(row >> 8) * 16 + (col >> 6)) * 256 + (row & 255)) << 6) + (col & 63); }
; __device__ __forceinline__ float bf2f(unsigned b) { return __uint_as_float(b << 16); }
;     __device__ __forceinline__ void operator()(const f32x4 (&acc)[2][2][4][2], const pg8::Unit& u, int wr, int wc, int fr, int fq) const {
;     ...
;         for (int ai = 0; ai < 2; ++ai) {
;             float ss[4] = {0.f, 0.f, 0.f, 0.f};
; #pragma unroll
;             for (int bj = 0; bj < 2; ++bj) {
;                 const int col = colb + 128 * bj;
;                 u32x4 xr[4]; f32x4 ga4[2];
; #pragma unroll
;                 for (int m = 0; m < 4; ++m) xr[m] = *(const GAS u32x4*)(xres + TX(row0 + 128 * ai + 16 * m, col));
; #pragma unroll
;                 for (int n = 0; n < 2; ++n) ga4[n] = *(const GAS f32x4*)(ga + col + 4 * n);
; #pragma unroll
;                 for (int m = 0; m < 4; ++m) {
;                     const size_t off = (size_t)(row0 + 128 * ai + 16 * m) * DM + col;
;                     const f32x4 x0 = {bf2f(xr[m].x & 0xffffu), bf2f(xr[m].x >> 16), bf2f(xr[m].y & 0xffffu), bf2f(xr[m].y >> 16)};
;                     const f32x4 x1 = {bf2f(xr[m].z & 0xffffu), bf2f(xr[m].z >> 16), bf2f(xr[m].w & 0xffffu), bf2f(xr[m].w >> 16)};
;                     const f32x4 n0 = x0 + ga4[0] * acc[ai][bj][m][0], n1 = x1 + ga4[1] * acc[ai][bj][m][1];
;                     if (NXT) {
;                         u32x4 w; w.x = cvt_pk_bf16(n0[0], n0[1]); w.y = cvt_pk_bf16(n0[2], n0[3]); w.z = cvt_pk_bf16(n1[0], n1[1]); w.w = cvt_pk_bf16(n1[2], n1[3]);
;                         *(GAS u32x4*)(xres + TX(row0 + 128 * ai + 16 * m, col)) = w;
;                         { const f32x4 q = n0 * n0 + n1 * n1; ss[m] += (q[0] + q[1]) + (q[2] + q[3]); }
.LBB0_489:
	s_or_b64 exec, exec, s[18:19]
	v_add_u32_e32 v68, 0x80, v164
	v_ashrrev_i32_e32 v66, 8, v68
	s_waitcnt lgkmcnt(0)
	v_ashrrev_i32_e32 v67, 31, v66
	v_lshlrev_b64 v[84:85], 12, v[66:67]
	v_and_b32_e32 v95, 0xcf, v68
	v_lshl_add_u64 v[66:67], v[84:85], 0, s[16:17]
	v_or_b32_e32 v68, v66, v95
	v_mov_b32_e32 v69, v67
	v_lshlrev_b64 v[108:109], 7, v[68:69]
	v_lshl_add_u64 v[68:69], v[162:163], 0, v[108:109]
	v_or_b32_e32 v96, 16, v95
	v_or_b32_e32 v68, v66, v96
	v_mov_b32_e32 v69, v67
	v_lshlrev_b64 v[90:91], 7, v[68:69]
	v_lshl_add_u64 v[68:69], v[162:163], 0, v[90:91]
	v_or_b32_e32 v97, 32, v95
	v_or_b32_e32 v98, 48, v95
	v_or_b32_e32 v68, v66, v97
	v_mov_b32_e32 v69, v67
	v_or_b32_e32 v66, v66, v98
	v_lshlrev_b64 v[88:89], 7, v[68:69]
	v_lshlrev_b64 v[86:87], 7, v[66:67]
	v_lshl_add_u64 v[68:69], v[162:163], 0, v[88:89]
	v_lshl_add_u64 v[66:67], v[162:163], 0, v[86:87]
	s_nop 0
	v_lshl_add_u64 v[108:109], s[20:21], 0, v[108:109]
	v_lshl_add_u64 v[108:109], v[108:109], 0, v[178:179]
	s_waitcnt vmcnt(14)
	v_mov_b32_e32 v100, v154
	v_mov_b32_e32 v101, v155
	v_mov_b32_e32 v102, v156
	v_mov_b32_e32 v103, v157
	v_mov_b32_e32 v104, v158
	v_mov_b32_e32 v105, v159
	v_mov_b32_e32 v106, v160
	v_mov_b32_e32 v107, v161
	v_mov_b32_e32 v78, v228
	v_mov_b32_e32 v79, v229
	v_mov_b32_e32 v80, v230
	v_mov_b32_e32 v81, v231
	v_mov_b32_e32 v74, v234
	v_mov_b32_e32 v75, v235
	v_mov_b32_e32 v76, v236
	v_mov_b32_e32 v77, v237
	v_mov_b32_e32 v66, v242
	v_mov_b32_e32 v67, v243
	v_mov_b32_e32 v68, v244
	v_mov_b32_e32 v69, v245
	v_mov_b32_e32 v70, v246
	v_mov_b32_e32 v71, v247
	v_mov_b32_e32 v72, v248
	v_mov_b32_e32 v73, v249
	v_lshlrev_b32_e32 v110, 16, v100
	v_and_b32_e32 v111, 0xffff0000, v100
	v_lshlrev_b32_e32 v100, 16, v101
	v_and_b32_e32 v101, 0xffff0000, v101
	v_lshlrev_b32_e32 v112, 16, v102
	v_and_b32_e32 v113, 0xffff0000, v102
	v_lshlrev_b32_e32 v102, 16, v103
	v_and_b32_e32 v103, 0xffff0000, v103
	v_pk_fma_f32 v[64:65], v[64:65], v[72:73], v[100:101]
	v_pk_fma_f32 v[62:63], v[62:63], v[70:71], v[110:111]
	v_pk_fma_f32 v[100:101], v[60:61], v[68:69], v[102:103]
	v_pk_fma_f32 v[102:103], v[58:59], v[66:67], v[112:113]
	v_cvt_pk_bf16_f32 v58, v62, v63
	v_cvt_pk_bf16_f32 v59, v64, v65
	s_nop 0
	v_cvt_pk_bf16_f32 v60, v102, v103
	v_cvt_pk_bf16_f32 v61, v100, v101
	global_store_dwordx4 v[108:109], v[58:61], off
	s_nop 1
	v_pk_mul_f32 v[58:59], v[102:103], v[102:103]
	v_pk_mul_f32 v[60:61], v[100:101], v[100:101]
	v_pk_fma_f32 v[58:59], v[62:63], v[62:63], v[58:59]
	v_pk_fma_f32 v[60:61], v[64:65], v[64:65], v[60:61]
	v_add_f32_e32 v58, v58, v59
	v_add_f32_e32 v59, v60, v61
	v_lshlrev_b32_e32 v62, 16, v106
	v_and_b32_e32 v63, 0xffff0000, v106
	v_add_f32_e32 v94, v58, v59
	v_lshlrev_b32_e32 v58, 16, v104
	v_and_b32_e32 v59, 0xffff0000, v104
	v_lshlrev_b32_e32 v60, 16, v105
	v_and_b32_e32 v61, 0xffff0000, v105
	v_lshlrev_b32_e32 v64, 16, v107
	v_and_b32_e32 v65, 0xffff0000, v107
	v_pk_fma_f32 v[50:51], v[50:51], v[66:67], v[62:63]
	v_lshl_add_u64 v[62:63], s[20:21], 0, v[90:91]
	v_pk_fma_f32 v[56:57], v[56:57], v[72:73], v[60:61]
	v_pk_fma_f32 v[54:55], v[54:55], v[70:71], v[58:59]
	v_pk_fma_f32 v[52:53], v[52:53], v[68:69], v[64:65]
	v_cvt_pk_bf16_f32 v58, v54, v55
	v_cvt_pk_bf16_f32 v59, v56, v57
	v_cvt_pk_bf16_f32 v60, v50, v51
	v_lshl_add_u64 v[62:63], v[62:63], 0, v[178:179]
	v_cvt_pk_bf16_f32 v61, v52, v53
	global_store_dwordx4 v[62:63], v[58:61], off
	v_lshlrev_b32_e32 v64, 16, v80
	v_and_b32_e32 v65, 0xffff0000, v80
	v_lshlrev_b32_e32 v60, 16, v78
	v_and_b32_e32 v61, 0xffff0000, v78
	v_lshlrev_b32_e32 v58, 16, v79
	v_and_b32_e32 v59, 0xffff0000, v79
	v_pk_fma_f32 v[60:61], v[46:47], v[70:71], v[60:61]
	v_lshl_add_u64 v[46:47], s[20:21], 0, v[88:89]
	v_lshlrev_b32_e32 v62, 16, v81
	v_and_b32_e32 v63, 0xffff0000, v81
	v_pk_fma_f32 v[58:59], v[48:49], v[72:73], v[58:59]
	v_pk_fma_f32 v[64:65], v[42:43], v[66:67], v[64:65]
	v_cvt_pk_bf16_f32 v42, v60, v61
	v_cvt_pk_bf16_f32 v43, v58, v59
	v_lshl_add_u64 v[46:47], v[46:47], 0, v[178:179]
	v_pk_fma_f32 v[62:63], v[44:45], v[68:69], v[62:63]
	v_cvt_pk_bf16_f32 v44, v64, v65
	v_lshlrev_b32_e32 v48, 16, v77
	v_cvt_pk_bf16_f32 v45, v62, v63
	global_store_dwordx4 v[46:47], v[42:45], off
	v_lshlrev_b32_e32 v46, 16, v76
	v_and_b32_e32 v47, 0xffff0000, v76
	v_lshlrev_b32_e32 v42, 16, v74
	v_and_b32_e32 v43, 0xffff0000, v74
	v_lshlrev_b32_e32 v44, 16, v75
	v_and_b32_e32 v45, 0xffff0000, v75
	v_pk_fma_f32 v[70:71], v[38:39], v[70:71], v[42:43]
	v_lshl_add_u64 v[38:39], s[20:21], 0, v[86:87]
	v_and_b32_e32 v49, 0xffff0000, v77
	v_pk_fma_f32 v[72:73], v[40:41], v[72:73], v[44:45]
	v_pk_fma_f32 v[66:67], v[34:35], v[66:67], v[46:47]
	v_cvt_pk_bf16_f32 v34, v70, v71
	v_cvt_pk_bf16_f32 v35, v72, v73
	v_lshl_add_u64 v[38:39], v[38:39], 0, v[178:179]
	v_pk_fma_f32 v[68:69], v[36:37], v[68:69], v[48:49]
	v_cvt_pk_bf16_f32 v36, v66, v67
	s_nop 0
	v_cvt_pk_bf16_f32 v37, v68, v69
	global_store_dwordx4 v[38:39], v[34:37], off
	s_nop 1
	v_lshl_add_u64 v[34:35], v[84:85], 0, v[120:121]
	v_or_b32_e32 v36, v34, v95
	v_mov_b32_e32 v37, v35
	v_lshlrev_b64 v[80:81], 7, v[36:37]
	v_lshl_add_u64 v[36:37], v[162:163], 0, v[80:81]
	v_or_b32_e32 v36, v34, v96
	v_mov_b32_e32 v37, v35
	v_lshlrev_b64 v[78:79], 7, v[36:37]
	v_lshl_add_u64 v[36:37], v[162:163], 0, v[78:79]
	v_or_b32_e32 v36, v34, v97
	v_mov_b32_e32 v37, v35
	v_or_b32_e32 v34, v34, v98
	v_lshlrev_b64 v[76:77], 7, v[36:37]
	v_lshlrev_b64 v[74:75], 7, v[34:35]
	v_lshl_add_u64 v[36:37], v[162:163], 0, v[76:77]
	v_lshl_add_u64 v[34:35], v[162:163], 0, v[74:75]
	s_nop 0
	v_lshl_add_u64 v[80:81], s[20:21], 0, v[80:81]
	v_lshl_add_u64 v[80:81], v[80:81], 0, v[178:179]
	s_waitcnt vmcnt(8)
; __device__ __forceinline__ unsigned cvt_pk_bf16(float lo, float hi) { unsigned r; asm volatile("v_cvt_pk_bf16_f32 %0, %1, %2" : "=v"(r) : "v"(lo), "v"(hi)); return r; }
; #define GAS __attribute__((address_space(1)))
; __device__ __forceinline__ size_t TX(int row, int col) { return ((((size_t)(row >> 8) * 16 + (col >> 6)) * 256 + (row & 255)) << 6) + (col & 63); }
; __device__ __forceinline__ float bf2f(unsigned b) { return __uint_as_float(b << 16); }
;     __device__ __forceinline__ void operator()(const f32x4 (&acc)[2][2][4][2], const pg8::Unit& u, int wr, int wc, int fr, int fq) const {
;     ...
;                 for (int m = 0; m < 4; ++m) {
;                     const size_t off = (size_t)(row0 + 128 * ai + 16 * m) * DM + col;
;                     const f32x4 x0 = {bf2f(xr[m].x & 0xffffu), bf2f(xr[m].x >> 16), bf2f(xr[m].y & 0xffffu), bf2f(xr[m].y >> 16)};
;                     const f32x4 x1 = {bf2f(xr[m].z & 0xffffu), bf2f(xr[m].z >> 16), bf2f(xr[m].w & 0xffffu), bf2f(xr[m].w >> 16)};
;                     const f32x4 n0 = x0 + ga4[0] * acc[ai][bj][m][0], n1 = x1 + ga4[1] * acc[ai][bj][m][1];
;                     if (NXT) {
;                         u32x4 w; w.x = cvt_pk_bf16(n0[0], n0[1]); w.y = cvt_pk_bf16(n0[2], n0[3]); w.z = cvt_pk_bf16(n1[0], n1[1]); w.w = cvt_pk_bf16(n1[2], n1[3]);
;                         *(GAS u32x4*)(xres + TX(row0 + 128 * ai + 16 * m, col)) = w;
;                         { const f32x4 q = n0 * n0 + n1 * n1; ss[m] += (q[0] + q[1]) + (q[2] + q[3]); }
;                     } else { *(GAS f32x4*)(fout + off) = n0; *(GAS f32x4*)(fout + off + 4) = n1; }
;                 }
;             }
;             if (NXT) {
; #pragma unroll
;                 for (int m = 0; m < 4; ++m) { float s = ss[m]; s += __shfl_xor(s, 16); s += __shfl_xor(s, 32);
;                     if (fq == 0) __hip_atomic_fetch_add(ssq_out + row0 + 128 * ai + 16 * m, (unsigned)(s * 1024.0f + 0.5f), __ATOMIC_RELAXED, __HIP_MEMORY_SCOPE_AGENT); }
	v_mov_b32_e32 v84, v200
	v_mov_b32_e32 v85, v201
	v_mov_b32_e32 v86, v202
	v_mov_b32_e32 v87, v203
	v_mov_b32_e32 v88, v204
	v_mov_b32_e32 v89, v205
	v_mov_b32_e32 v90, v206
	v_mov_b32_e32 v91, v207
	v_mov_b32_e32 v42, v208
	v_mov_b32_e32 v43, v209
	v_mov_b32_e32 v44, v210
	v_mov_b32_e32 v45, v211
	v_mov_b32_e32 v38, v212
	v_mov_b32_e32 v39, v213
	v_mov_b32_e32 v40, v214
	v_mov_b32_e32 v41, v215
	v_mov_b32_e32 v34, v216
	v_mov_b32_e32 v35, v217
	v_mov_b32_e32 v36, v218
	v_mov_b32_e32 v37, v219
	v_mov_b32_e32 v46, v150
	v_mov_b32_e32 v47, v151
	v_mov_b32_e32 v48, v152
	v_mov_b32_e32 v49, v153
	v_lshlrev_b32_e32 v96, 16, v84
	v_and_b32_e32 v97, 0xffff0000, v84
	v_lshlrev_b32_e32 v84, 16, v85
	v_and_b32_e32 v85, 0xffff0000, v85
	v_lshlrev_b32_e32 v98, 16, v86
	v_and_b32_e32 v99, 0xffff0000, v86
	v_lshlrev_b32_e32 v86, 16, v87
	v_and_b32_e32 v87, 0xffff0000, v87
	v_pk_fma_f32 v[32:33], v[32:33], v[48:49], v[84:85]
	v_pk_fma_f32 v[30:31], v[30:31], v[46:47], v[96:97]
	v_pk_fma_f32 v[84:85], v[28:29], v[36:37], v[86:87]
	v_pk_fma_f32 v[86:87], v[26:27], v[34:35], v[98:99]
	v_cvt_pk_bf16_f32 v26, v30, v31
	v_cvt_pk_bf16_f32 v27, v32, v33
	s_nop 0
	v_cvt_pk_bf16_f32 v28, v86, v87
	v_cvt_pk_bf16_f32 v29, v84, v85
	global_store_dwordx4 v[80:81], v[26:29], off
	s_nop 1
	v_pk_mul_f32 v[26:27], v[86:87], v[86:87]
	v_pk_mul_f32 v[28:29], v[84:85], v[84:85]
	v_pk_fma_f32 v[26:27], v[30:31], v[30:31], v[26:27]
	v_pk_fma_f32 v[28:29], v[32:33], v[32:33], v[28:29]
	v_add_f32_e32 v26, v26, v27
	v_add_f32_e32 v27, v28, v29
	v_lshlrev_b32_e32 v28, 16, v89
	v_and_b32_e32 v29, 0xffff0000, v89
	v_lshlrev_b32_e32 v30, 16, v90
	v_and_b32_e32 v31, 0xffff0000, v90
	v_add_f32_e32 v26, v26, v27
	v_pk_fma_f32 v[24:25], v[24:25], v[48:49], v[28:29]
	v_pk_fma_f32 v[28:29], v[18:19], v[34:35], v[30:31]
	v_lshl_add_u64 v[30:31], s[20:21], 0, v[78:79]
	v_add_f32_e32 v80, v94, v26
	v_lshlrev_b32_e32 v26, 16, v88
	v_and_b32_e32 v27, 0xffff0000, v88
	v_lshlrev_b32_e32 v32, 16, v91
	v_and_b32_e32 v33, 0xffff0000, v91
	v_lshl_add_u64 v[30:31], v[30:31], 0, v[178:179]
	v_pk_fma_f32 v[22:23], v[22:23], v[46:47], v[26:27]
	v_pk_fma_f32 v[26:27], v[20:21], v[36:37], v[32:33]
	v_cvt_pk_bf16_f32 v18, v22, v23
	v_cvt_pk_bf16_f32 v19, v24, v25
	v_cvt_pk_bf16_f32 v20, v28, v29
	v_lshlrev_b32_e32 v32, 16, v45
	v_cvt_pk_bf16_f32 v21, v26, v27
	global_store_dwordx4 v[30:31], v[18:21], off
	v_lshlrev_b32_e32 v30, 16, v44
	v_and_b32_e32 v31, 0xffff0000, v44
	v_pk_fma_f32 v[10:11], v[10:11], v[34:35], v[30:31]
	v_lshl_add_u64 v[30:31], s[20:21], 0, v[76:77]
	v_lshlrev_b32_e32 v18, 16, v42
	v_and_b32_e32 v19, 0xffff0000, v42
	v_lshlrev_b32_e32 v20, 16, v43
	v_and_b32_e32 v21, 0xffff0000, v43
	v_and_b32_e32 v33, 0xffff0000, v45
	v_lshl_add_u64 v[30:31], v[30:31], 0, v[178:179]
	v_pk_fma_f32 v[16:17], v[16:17], v[48:49], v[20:21]
	v_pk_fma_f32 v[14:15], v[14:15], v[46:47], v[18:19]
	v_pk_fma_f32 v[12:13], v[12:13], v[36:37], v[32:33]
	v_cvt_pk_bf16_f32 v18, v14, v15
	v_cvt_pk_bf16_f32 v19, v16, v17
	v_cvt_pk_bf16_f32 v20, v10, v11
	v_lshlrev_b32_e32 v32, 16, v41
	v_cvt_pk_bf16_f32 v21, v12, v13
	global_store_dwordx4 v[30:31], v[18:21], off
	v_lshlrev_b32_e32 v30, 16, v40
	v_and_b32_e32 v31, 0xffff0000, v40
	v_lshlrev_b32_e32 v18, 16, v38
	v_and_b32_e32 v19, 0xffff0000, v38
	v_pk_fma_f32 v[2:3], v[2:3], v[34:35], v[30:31]
	v_lshl_add_u64 v[30:31], s[20:21], 0, v[74:75]
	v_lshlrev_b32_e32 v20, 16, v39
	v_and_b32_e32 v21, 0xffff0000, v39
	v_and_b32_e32 v33, 0xffff0000, v41
	v_pk_fma_f32 v[6:7], v[6:7], v[46:47], v[18:19]
	v_lshl_add_u64 v[30:31], v[30:31], 0, v[178:179]
	v_cvt_pk_bf16_f32 v18, v6, v7
	v_pk_fma_f32 v[8:9], v[8:9], v[48:49], v[20:21]
	v_pk_fma_f32 v[4:5], v[4:5], v[36:37], v[32:33]
	v_cvt_pk_bf16_f32 v19, v8, v9
	v_cvt_pk_bf16_f32 v20, v2, v3
	s_nop 0
	v_cvt_pk_bf16_f32 v21, v4, v5
	global_store_dwordx4 v[30:31], v[18:21], off
	ds_bpermute_b32 v18, v92, v80
	s_waitcnt lgkmcnt(0)
	v_add_f32_e32 v18, v80, v18
	ds_bpermute_b32 v19, v93, v18
	s_and_saveexec_b64 s[16:17], s[0:1]
	s_cbranch_execz .LBB0_491
	s_waitcnt lgkmcnt(0)
	v_add_f32_e32 v18, v18, v19
	v_fma_f32 v18, v18, s72, 0.5
	v_cvt_u32_f32_e32 v18, v18
	global_atomic_add v[82:83], v18, off offset:512
